# rw_scan: stage-B hand schedule (scalar role branch, batched LDS, LDS-free Tinv via readlane), P1 front LDS batching, permlane-swap reductions, Tinv waves one per SIMD
# speedup vs baseline: 1.0331x; 1.0331x over previous
; #define LAS __attribute__((address_space(3)))
; __device__ __forceinline__ void rw_scan(LAS unsigned char* L, const bf16_t* Rg, const bf16_t* Kg, const bf16_t* Vg, const bf16_t* VF, const bf16_t* LO, const bf16_t* wlbT, const bf16_t* albT, const bf16_t* vlbT, ...
;     ...
;     const int tid = otid(), wid = tid >> 6, lane = tid & 63, fr = lane & 15, fq = lane >> 4;
;     const bool hasvf = VF != nullptr;
;     const bf16x8 zero8 = (bf16x8){0, 0, 0, 0, 0, 0, 0, 0};
;     for (int wk0 = obid(); wk0 < 256; wk0 += gridDim.x) {
;         const int wk = ((wk0 & 7) << 5) | (wk0 >> 3);
;         const int chain = wk >> 2, q = wk & 3, g = chain >> 5, b = (chain >> 4) & 1, h = chain & 15;
;         { const int tid2 = otid(); const int d = tid2 >> 3, sg = tid2 & 7;
;             *(LAS bf16x8*)(BTw + d * 72 + sg * 8) = *(const bf16x8*)(wlbT + ((size_t)g * 1024 + h * 64 + d) * 64 + sg * 8);
;             *(LAS bf16x8*)(BTa + d * 72 + sg * 8) = *(const bf16x8*)(albT + ((size_t)g * 1024 + h * 64 + d) * 64 + sg * 8);
;             if (hasvf && tid2 < 256) { const int d2 = tid2 >> 2, s2 = tid2 & 3; *(LAS bf16x8*)(BTv + d2 * 40 + s2 * 8) = *(const bf16x8*)(vlbT + (size_t)(h * 64 + d2) * 32 + s2 * 8); }
;             if (tid2 < 384) { const int arr = tid2 >> 6, d3 = tid2 & 63, col = h * 64 + d3;
;                 float v = 0.f; if (arr == 0) v = w0[g * 1024 + col]; else if (arr == 1) v = hasvf ? v0[col] : 0.f; else if (arr == 2) v = a0[g * 1024 + col]; else if (arr == 3) v = k_k[col]; else if (arr == 4) v = k_a[col]; else v = r_k[col];
;                 CSTb[arr * 64 + d3] = v; }
;             for (int idx = tid2; idx < 4096; idx += 512) { const int st = idx >> 11, w = idx & 2047;
;                 ((LAS unsigned*)(L + SET0 + st * SETSZ + (w < 1024 ? 35840 : 45056 - 4096)))[w] = 0u; } }
;         __syncthreads();
;         const int ti = wid & 3, half = wid >> 2;
;         const int cb = h * 64 + 4 * fq;
;         const bool hasv = (half == 1);
;         bf16x8 flw0, flw1, fla0, fla1, flv = zero8; u32x2 xK[4], xR[2], xV = (u32x2){0u, 0u}, xVF = (u32x2){0u, 0u}; size_t rowg = 0;
;     ...
;             if (m < 256) { const int sc = wid >> 1;
; #pragma unroll
;                 for (int ml = 0; ml < 3; ++ml) { const int mat = (wid & 1) ? ml + 1 : 0; if ((wid & 1) == 0 && ml > 0) break;     const LAS bf16_t* Am = (mat < 2) ? KQ : RQ; const LAS bf16_t* Bm = (mat & 1) ? KD : BD;
.LBB0_38:
	s_cmp_gt_i32 s83, 1
	s_cbranch_scc0 .LBB0_206
	s_cmp_eq_u32 s83, 2
	s_mov_b64 s[44:45], -1
	s_cbranch_scc0 .LBB0_205
	v_writelane_b32 v254, s68, 53
	v_mov_b32_e32 v1, v196
	s_mov_b32 s1, s82
	v_writelane_b32 v254, s69, 54
	v_writelane_b32 v254, s66, 47
	s_cmpk_gt_i32 s1, 0xff
	s_nop 0
	v_writelane_b32 v254, s67, 48
	v_writelane_b32 v254, s16, 55
	s_nop 1
	v_writelane_b32 v254, s17, 56
	s_cbranch_scc1 .LBB0_204
	s_lshl_b32 s4, s95, 11
	s_ashr_i32 s5, s4, 31
	v_readlane_b32 s40, v253, 33
	s_lshl_b64 s[4:5], s[4:5], 2
	v_readlane_b32 s42, v253, 35
	v_readlane_b32 s43, v253, 36
	s_add_u32 s2, s42, s4
	s_addc_u32 s3, s43, s5
	v_readlane_b32 s48, v253, 41
	v_writelane_b32 v254, s2, 57
	v_readlane_b32 s49, v253, 42
	v_readlane_b32 s41, v253, 34
	v_writelane_b32 v254, s3, 58
	s_add_u32 s2, s48, s4
	v_readlane_b32 s44, v253, 37
	v_readlane_b32 s45, v253, 38
	v_readlane_b32 s46, v253, 39
	v_readlane_b32 s47, v253, 40
	v_readlane_b32 s50, v253, 43
	v_readlane_b32 s51, v253, 44
	v_readlane_b32 s52, v253, 45
	v_readlane_b32 s53, v253, 46
	v_readlane_b32 s54, v253, 47
	v_readlane_b32 s55, v253, 48
	s_addc_u32 s3, s49, s5
	s_lshl_b32 s4, s95, 10
	s_ashr_i32 s5, s4, 31
	v_readlane_b32 s40, v253, 49
	v_writelane_b32 v254, s2, 59
	s_lshl_b64 s[4:5], s[4:5], 2
	v_readlane_b32 s48, v253, 57
	v_writelane_b32 v254, s3, 60
	v_readlane_b32 s49, v253, 58
	s_add_u32 s2, s48, s4
	s_addc_u32 s3, s49, s5
	v_readlane_b32 s50, v253, 59
	v_readlane_b32 s55, v254, 0
	v_writelane_b32 v254, s2, 61
	v_readlane_b32 s51, v253, 60
	v_readlane_b32 s52, v253, 61
	v_writelane_b32 v254, s3, 62
	s_add_u32 s2, s50, s4
	s_addc_u32 s3, s51, s5
	v_writelane_b32 v254, s2, 63
	v_readlane_b32 s53, v253, 62
	v_ashrrev_i32_e32 v67, 8, v1
	v_writelane_b32 v255, s3, 0
	s_add_u32 s2, s52, s4
	s_addc_u32 s3, s53, s5
	v_writelane_b32 v255, s2, 1
	v_and_b32_e32 v2, 63, v1
	v_bfe_u32 v65, v1, 6, 2
	v_writelane_b32 v255, s3, 2
	v_readlane_b32 s2, v254, 45
	v_readlane_b32 s3, v254, 46
	s_add_u32 s12, s2, 0x1000000
	s_addc_u32 s13, s3, 0
	s_add_u32 s16, s2, 0x1040000
	s_addc_u32 s17, s3, 0
	v_cmp_ne_u32_e64 s[2:3], 1, v67
	s_waitcnt vmcnt(0)
	v_lshlrev_b32_e32 v10, 1, v1
	v_and_b32_e32 v61, 15, v1
	v_writelane_b32 v255, s2, 3
	v_lshlrev_b32_e32 v4, 4, v65
	v_cmp_gt_u32_e64 s[48:49], 16, v2
	v_writelane_b32 v255, s3, 4
	s_movk_i32 s2, 0x3fff
	v_ashrrev_i32_e32 v13, 3, v1
	v_and_b32_e32 v2, 14, v10
	v_readlane_b32 s42, v253, 51
	v_readlane_b32 s43, v253, 52
	v_bitop3_b32 v140, v4, s2, v61 bitop3:0x36
	v_readlane_b32 s2, v254, 49
	v_and_b32_e32 v11, 6, v10
	v_add_u32_e32 v142, 0xffffff80, v13
	v_mul_lo_u32 v10, v13, 36
	v_lshlrev_b32_e32 v13, 1, v2
	v_readlane_b32 s41, v253, 50
	v_cmp_eq_u32_e64 s[42:43], 1, v67
	v_readlane_b32 s3, v254, 50
	v_add3_u32 v143, 0, v10, v13
	v_bfe_u32 v10, v1, 6, 2
	v_lshrrev_b32_e32 v13, 2, v1
	v_and_b32_e32 v13, 64, v13
	v_readlane_b32 s46, v253, 55
	v_readlane_b32 s47, v253, 56
	s_and_b64 s[40:41], s[2:3], s[42:43]
	v_lshlrev_b32_e32 v62, 5, v67
	v_and_b32_e32 v64, 48, v1
	s_movk_i32 s2, 0x100
	v_cmp_ne_u32_e64 s[50:51], 0, v13
	v_lshlrev_b32_e32 v14, 4, v10
	v_cmp_eq_u32_e32 vcc, 0, v13
	v_mov_b32_e32 v13, 0x8600
	v_mov_b32_e32 v19, 0x6200
	s_waitcnt lgkmcnt(0)
; __device__ __forceinline__ bf16_t f2bf(float f) { return (bf16_t)(cvt_pk_bf16(f, 0.f) & 0xffffu); }
; __device__ __forceinline__ void rw_scan(LAS unsigned char* L, const bf16_t* Rg, const bf16_t* Kg, const bf16_t* Vg, const bf16_t* VF, const bf16_t* LO, const bf16_t* wlbT, const bf16_t* albT, const bf16_t* vlbT, ...
;     ...
;         const int ti = wid & 3, half = wid >> 2;
;         const int cb = h * 64 + 4 * fq;
;         const bool hasv = (half == 1);
;         bf16x8 flw0, flw1, fla0, fla1, flv = zero8; u32x2 xK[4], xR[2], xV = (u32x2){0u, 0u}, xVF = (u32x2){0u, 0u}; size_t rowg = 0;
;     ...
;                     for (int r = 0; r < 4; ++r) { const int t = 4 * fq + r, sidx = fr; const bool keep = (mat < 2) ? (sidx < t) : (sidx <= t); const float val = keep ? acc[r] : 0.f;
;                         if (mat == 0) MM[(sc * 16 + t) * 20 + sidx] = val;
;                         else if (mat == 1) NA[(sc * 16 + t) * 32 + 8 * (sidx >> 2) + 4 + (sidx & 3)] = f2bf(val);
;                         else if (mat == 2) AR[(sc * 16 + t) * 40 + 8 * (sidx >> 2) + 2 * (sidx & 3)] = f2bf(val);
;                         else AR[(sc * 16 + t) * 40 + 8 * (sidx >> 2) + 2 * (sidx & 3) + 1] = f2bf(val); } }
;                 if ((wid & 1) == 0) { asm volatile("" ::: "memory");
;                     const int c = lane & 15; float tcol[16];
; #pragma unroll
;                     for (int i = 0; i < 16; ++i) { float acc0 = (i == c) ? 1.f : 0.f, acc1 = 0.f;
	v_bfe_u32 v3, v1, 4, 2
	v_add_u32_e32 v66, 0, v64
	v_or_b32_e32 v5, v62, v61
	v_cmp_gt_u32_e64 s[46:47], s2, v1
	v_or_b32_e32 v15, v14, v61
	s_movk_i32 s2, 0x90
	v_cndmask_b32_e32 v13, v13, v19, vcc
	v_lshlrev_b32_e32 v138, 2, v3
	v_mad_u64_u32 v[68:69], s[4:5], v5, s2, v[66:67]
	v_add_u32_e32 v13, 0, v13
	v_mul_lo_u32 v15, v15, s2
	v_add3_u32 v146, v13, v15, v64
	v_or_b32_e32 v13, v138, v14
	s_movk_i32 s5, 0x50
	v_lshlrev_b32_e32 v147, 6, v13
	v_mul_lo_u32 v148, v13, s5
	v_or_b32_e32 v13, 1, v138
	v_cmp_eq_u32_e32 vcc, 1, v61
	v_or_b32_e32 v19, v13, v14
	v_lshlrev_b32_e32 v149, 6, v19
	v_cndmask_b32_e64 v158, 0, 1.0, vcc
	v_cmp_eq_u32_e32 vcc, 2, v61
	v_mul_lo_u32 v150, v19, s5
	v_or_b32_e32 v19, 2, v138
	s_movk_i32 s4, 0x500
	v_cndmask_b32_e64 v160, 0, 1.0, vcc
	v_cmp_eq_u32_e32 vcc, 3, v61
	v_or_b32_e32 v6, v138, v62
	v_lshlrev_b32_e32 v9, 6, v65
	v_lshlrev_b32_e32 v16, 10, v10
	v_or_b32_e32 v20, v19, v14
	v_mul_lo_u32 v10, v10, s4
	v_cndmask_b32_e64 v161, 0, 1.0, vcc
	v_cmp_eq_u32_e32 vcc, 4, v61
	v_readlane_b32 s4, v252, 51
	v_readlane_b32 s44, v253, 53
	v_readlane_b32 s45, v253, 54
	v_or_b32_e32 v139, v4, v61
	v_lshlrev_b32_e32 v12, 8, v65
	v_lshlrev_b32_e32 v5, 2, v6
	v_lshlrev_b32_e32 v151, 6, v20
	v_mul_lo_u32 v152, v20, s5
	v_or_b32_e32 v20, 3, v138
	v_add_u32_e32 v159, 0, v10
	v_cndmask_b32_e64 v162, 0, 1.0, vcc
	v_cmp_eq_u32_e32 vcc, 5, v61
	v_add_u32_e32 v10, s4, v9
	v_readlane_b32 s4, v252, 52
	v_cmp_gt_u32_e64 s[44:45], 64, v1
	v_or_b32_e32 v17, 48, v1
	v_or_b32_e32 v14, v20, v14
	v_cndmask_b32_e64 v163, 0, 1.0, vcc
	v_cmp_eq_u32_e32 vcc, 6, v61
	v_lshlrev_b32_e32 v1, 2, v1
	v_add3_u32 v175, s4, v12, v5
	v_lshlrev_b32_e32 v21, 1, v139
	v_readlane_b32 s4, v252, 53
	v_lshlrev_b32_e32 v153, 6, v14
	v_mul_lo_u32 v155, v14, s5
	v_cndmask_b32_e64 v164, 0, 1.0, vcc
	v_cmp_eq_u32_e32 vcc, 7, v61
	v_and_b32_e32 v1, 48, v1
	v_lshlrev_b32_e32 v14, 1, v11
	v_add_u32_e32 v22, s4, v21
	v_readlane_b32 s4, v252, 54
	v_cndmask_b32_e64 v165, 0, 1.0, vcc
	v_cmp_eq_u32_e32 vcc, 8, v61
	v_add3_u32 v176, s4, v1, v14
	v_readlane_b32 s4, v252, 55
	v_lshlrev_b32_e32 v60, 3, v3
	v_cndmask_b32_e64 v166, 0, 1.0, vcc
	v_cmp_eq_u32_e32 vcc, 9, v61
	v_add3_u32 v177, s4, v1, v11
	s_add_i32 s4, 0, 0x18000
	v_or_b32_e32 v7, v60, v62
	v_mul_u32_u24_e32 v8, 0x48, v139
	v_cndmask_b32_e64 v167, 0, 1.0, vcc
	v_cmp_eq_u32_e32 vcc, 10, v61
	v_add_u32_e32 v23, s4, v16
	v_readlane_b32 s4, v252, 58
	v_readlane_b32 s7, v252, 59
	v_lshlrev_b32_e32 v8, 1, v8
	v_lshlrev_b32_e32 v7, 1, v7
	v_cndmask_b32_e64 v168, 0, 1.0, vcc
	v_cmp_eq_u32_e32 vcc, 11, v61
	v_add_u32_e32 v9, s4, v9
	v_readlane_b32 s4, v252, 56
	v_add3_u32 v181, s7, v12, v5
	v_readlane_b32 s7, v252, 60
	v_add_u32_e32 v69, 0, v5
	v_cndmask_b32_e64 v169, 0, 1.0, vcc
	v_cmp_eq_u32_e32 vcc, 12, v61
	v_add3_u32 v179, s4, v8, v7
	v_readlane_b32 s6, v252, 57
	v_add_u32_e32 v5, s7, v21
	v_readlane_b32 s7, v252, 61
	v_add3_u32 v184, s4, v15, v64
	v_readlane_b32 s4, v252, 63
	v_lshlrev_b32_e32 v4, 1, v61
	v_add3_u32 v145, 0, v8, v7
	s_movk_i32 s3, 0x110
	v_cmp_eq_u32_e64 s[58:59], 0, v61
	v_cndmask_b32_e64 v170, 0, 1.0, vcc
	v_cmp_eq_u32_e32 vcc, 13, v61
	v_add3_u32 v180, s6, v8, v7
	v_add3_u32 v182, s7, v1, v14
	v_readlane_b32 s7, v252, 62
	v_add_u32_e32 v7, s4, v16
	v_readlane_b32 s54, v253, 63
	v_mul_lo_u32 v6, v6, s3
	v_mul_u32_u24_e32 v18, 0x240, v3
	v_cndmask_b32_e64 v157, 0, 1.0, s[58:59]
	v_cndmask_b32_e64 v171, 0, 1.0, vcc
	v_cmp_eq_u32_e32 vcc, 14, v61
	v_cmp_eq_u32_e64 s[60:61], 15, v61
	v_add3_u32 v10, v10, v1, v14
	v_add3_u32 v178, v23, v1, v11
	v_add3_u32 v9, v9, v1, v14
	v_add3_u32 v183, s7, v1, v11
	v_add3_u32 v186, v7, v1, v11
	v_mad_u32_u24 v1, v3, s2, v4
	v_mad_u32_u24 v188, v61, s5, v64
	v_mad_u64_u32 v[70:71], s[4:5], v17, s3, v[64:65]
	v_or_b32_e32 v141, 64, v139
	v_add3_u32 v144, 0, v4, v4
	v_ashrrev_i32_e32 v63, 31, v62
	v_cmp_lt_u32_e64 s[52:53], v61, v138
	v_cmp_gt_u32_e64 s[54:55], v61, v138
	v_cmp_lt_u32_e64 s[56:57], v61, v19
	v_add_u32_e32 v156, v66, v15
	v_cndmask_b32_e64 v172, 0, 1.0, vcc
	v_cndmask_b32_e64 v173, 0, 1.0, s[60:61]
	v_cvt_pk_bf16_f32 v174, -v157, s0
	v_add3_u32 v185, s6, v15, v64
	v_add_u32_e32 v187, 0xc700, v1
	v_lshl_or_b32 v189, v61, 6, v64
	v_mad_u32_u24 v190, v61, s2, v64
	v_mad_u32_u24 v191, v61, s2, v60
	v_mad_u32_u24 v71, v61, s3, v64
	v_add_u32_e32 v192, 0xbe00, v1
	v_lshlrev_b32_e32 v72, 1, v2
	v_add_u32_e32 v193, v22, v18
	v_add_u32_e32 v194, v5, v18
	v_add_u32_e32 v195, v10, v6
	v_add_u32_e32 v223, v9, v6
	v_cmp_lt_u32_e64 s[62:63], v61, v20
	v_cmp_gt_u32_e64 s[64:65], v61, v13
	v_cmp_gt_u32_e64 s[66:67], v61, v19
	v_cmp_gt_u32_e64 s[68:69], v61, v20
	s_branch .LBB0_43

; #define LAS __attribute__((address_space(3)))
; __device__ __forceinline__ void rw_scan(LAS unsigned char* L, const bf16_t* Rg, const bf16_t* Kg, const bf16_t* Vg, const bf16_t* VF, const bf16_t* LO, const bf16_t* wlbT, const bf16_t* albT, const bf16_t* vlbT, ...
;     ...
;             if (wid == 0) __builtin_amdgcn_s_setprio(3);
;             if (wid == 0) {
;                 if (m >= 1 && m <= 256) {
;                     LAS unsigned char* sp = L + SET0 + ((m - 1) & 1) * SETSZ;
;                     const LAS bf16_t* cKQ = (const LAS bf16_t*)sp; const LAS bf16_t* cRQ = (const LAS bf16_t*)(sp + 9216); const LAS bf16_t* cW2 = (const LAS bf16_t*)(sp + 18432); const LAS bf16_t* cNA = (const LAS bf16_t*)(sp + 35840);
;                     const LAS bf16_t* cAR = (const LAS bf16_t*)(sp + 39936); const LAS bf16_t* cTI = (const LAS bf16_t*)(sp + 45056); const LAS float* cLL = (const LAS float*)(sp + 49152); const LAS bf16_t* cVt = (const LAS bf16_t*)(sp + 50176);
;                     LAS bf16_t* ob = OUTb + ((m - 1) & 1) * (64 * 18);
;                     const f32x4 z4 = {0.f, 0.f, 0.f, 0.f};
; #pragma unroll 2
;                     for (int sc = 0; sc < 4; ++sc) {
.LBB0_91:
	s_and_saveexec_b64 s[22:23], s[44:45]
	s_cbranch_execz .LBB0_95
	s_setprio 3
	s_cmp_eq_u32 s81, 0
	s_cbranch_scc1 .LBB0_95
	s_mov_b32 s24, 4
	v_mov_b32_e32 v52, v71
	v_mov_b32_e32 v53, v70
	v_mov_b32_e32 v54, v64
	v_mov_b32_e32 v55, v191
	v_mov_b32_e32 v56, v190
	v_mov_b32_e32 v57, v189
	v_mov_b32_e32 v58, v188
	v_mov_b32_e32 v59, v187

; #define LAS __attribute__((address_space(3)))
; __device__ __forceinline__ f32x4 mma16(bf16x8 a, bf16x8 b, f32x4 c) { return __builtin_amdgcn_mfma_f32_16x16x32_bf16(a, b, c, 0, 0, 0); }
; __device__ __forceinline__ f32x4 unpk4(u32x2 w) { return (f32x4){__uint_as_float(w.x << 16), __uint_as_float(w.x & 0xffff0000u), __uint_as_float(w.y << 16), __uint_as_float(w.y & 0xffff0000u)}; }
; __device__ __forceinline__ void rw_scan(LAS unsigned char* L, const bf16_t* Rg, const bf16_t* Kg, const bf16_t* Vg, const bf16_t* VF, const bf16_t* LO, const bf16_t* wlbT, const bf16_t* albT, const bf16_t* vlbT, ...
;     ...
;                 f32x4 accw[2], acca[2], accv = (f32x4){0.f, 0.f, 0.f, 0.f};
; #pragma unroll
;                 for (int tl = 0; tl < 2; ++tl) { const int td = 2 * half + tl; accw[tl] = (f32x4){0.f, 0.f, 0.f, 0.f}; acca[tl] = (f32x4){0.f, 0.f, 0.f, 0.f};
;                     accw[tl] = mma16(lfrag(BTw, 72, td * 16 + fr, 8 * fq), flw0, accw[tl]); accw[tl] = mma16(lfrag(BTw, 72, td * 16 + fr, 32 + 8 * fq), flw1, accw[tl]);
;                     acca[tl] = mma16(lfrag(BTa, 72, td * 16 + fr, 8 * fq), fla0, acca[tl]); acca[tl] = mma16(lfrag(BTa, 72, td * 16 + fr, 32 + 8 * fq), fla1, acca[tl]); }
;                 if (hasvf && hasv) accv = mma16(lfrag(BTv, 40, q * 16 + fr, 8 * fq), flv, accv);
;                 float n2 = 0.f;
; #pragma unroll
;                 for (int td = 0; td < 4; ++td) { const f32x4 kk_ = unpk4(xK[td]) * *(const LAS f32x4*)(CSTb + 192 + td * 16 + 4 * fq); n2 += (kk_[0] * kk_[0] + kk_[1] * kk_[1]) + (kk_[2] * kk_[2] + kk_[3] * kk_[3]); }
;                 n2 += __shfl_xor(n2, 16); n2 += __shfl_xor(n2, 32);
;                 const float inv = fminf(__builtin_amdgcn_rsqf(n2), 1e12f);
;                 const f32x4 krs0 = unpk4(half ? xK[2] : xK[0]), krs1 = unpk4(half ? xK[3] : xK[1]), r4s0 = unpk4(xR[0]), r4s1 = unpk4(xR[1]); const f32x4 v4u = unpk4(xV), vf4u = unpk4(xVF);
;                 asm volatile("" ::: "memory");
;                 if (m + 1 < 256) RW_LOADS(m + 1);
.LBB0_95:
	s_or_b64 exec, exec, s[22:23]
	s_cmpk_lt_u32 s81, 0x100
	s_cselect_b64 s[24:25], -1, 0
	s_cmpk_gt_u32 s81, 0xff
	s_cbranch_scc1 .LBB0_119
	v_add_u32_e32 v1, v66, v224
	ds_read_b128 v[212:215], v68
	ds_read_b128 v[216:219], v68 offset:64
	ds_read_b128 v[230:233], v68 offset:9216
	ds_read_b128 v[234:237], v68 offset:9280
	ds_read_b128 v[238:241], v68 offset:2304
	ds_read_b128 v[246:249], v68 offset:2368
	ds_read_b128 v[112:115], v68 offset:11520
	ds_read_b128 v[116:119], v68 offset:11584
	ds_read_b128 v[120:123], v66 offset:24320
	ds_read_b128 v[202:205], v66 offset:24384
	ds_read_b128 v[206:209], v66 offset:24448
	ds_read_b128 v[102:105], v66 offset:24512
	ds_read_b128 v[126:129], v69 offset:23552
	ds_read_b128 v[130:133], v69 offset:24064
	s_waitcnt vmcnt(9) lgkmcnt(13)
	v_mfma_f32_16x16x32_bf16 v[40:43], v[212:215], v[20:23], 0
	ds_read_b128 v[212:215], v1 offset:18432
	s_waitcnt vmcnt(8) lgkmcnt(13)
	v_mfma_f32_16x16x32_bf16 v[56:59], v[216:219], v[16:19], v[40:43]
	s_waitcnt vmcnt(7) lgkmcnt(12)
	v_mfma_f32_16x16x32_bf16 v[40:43], v[230:233], v[12:15], 0
	s_waitcnt vmcnt(6) lgkmcnt(11)
	v_mfma_f32_16x16x32_bf16 v[52:55], v[234:237], v[8:11], v[40:43]
	s_waitcnt lgkmcnt(10)
	v_mfma_f32_16x16x32_bf16 v[20:23], v[238:241], v[20:23], 0
	s_waitcnt lgkmcnt(9)
	v_mfma_f32_16x16x32_bf16 v[48:51], v[246:249], v[16:19], v[20:23]
	s_waitcnt lgkmcnt(8)
	v_mfma_f32_16x16x32_bf16 v[12:15], v[112:115], v[12:15], 0
	s_waitcnt lgkmcnt(7)
	v_mfma_f32_16x16x32_bf16 v[44:47], v[116:119], v[8:11], v[12:15]
	v_mov_b32_e32 v40, 0
	v_mov_b32_e32 v41, 0
	v_mov_b32_e32 v42, 0
	v_mov_b32_e32 v43, 0
	s_and_saveexec_b64 s[22:23], s[40:41]
	s_cbranch_execz .LBB0_98
	s_waitcnt lgkmcnt(0)
	v_mfma_f32_16x16x32_bf16 v[40:43], v[212:215], v[4:7], 0
.LBB0_98:
	s_or_b64 exec, exec, s[22:23]
	s_waitcnt vmcnt(5)
	v_lshlrev_b32_e32 v2, 16, v106
	v_and_b32_e32 v3, 0xffff0000, v106
	v_lshlrev_b32_e32 v12, 16, v107
	v_and_b32_e32 v13, 0xffff0000, v107
	s_waitcnt lgkmcnt(0)
	v_pk_mul_f32 v[2:3], v[120:121], v[2:3]
	v_pk_mul_f32 v[10:11], v[122:123], v[12:13]
	v_mul_f32_e32 v1, v3, v3
	v_fmac_f32_e32 v1, v2, v2
	v_mul_f32_e32 v2, v11, v11
	v_fmac_f32_e32 v2, v10, v10
	v_add_f32_e32 v1, v1, v2
	s_waitcnt vmcnt(4)
	v_lshlrev_b32_e32 v2, 16, v96
	v_and_b32_e32 v3, 0xffff0000, v96
	v_lshlrev_b32_e32 v12, 16, v97
	v_and_b32_e32 v13, 0xffff0000, v97
	s_waitcnt lgkmcnt(0)
	v_pk_mul_f32 v[2:3], v[202:203], v[2:3]
	v_pk_mul_f32 v[10:11], v[204:205], v[12:13]
	v_mul_f32_e32 v3, v3, v3
	v_fmac_f32_e32 v3, v2, v2
	v_mul_f32_e32 v2, v11, v11
	v_fmac_f32_e32 v2, v10, v10
	v_add_f32_e32 v2, v3, v2
	v_add_f32_e32 v1, v1, v2
	s_waitcnt vmcnt(3)
	v_lshlrev_b32_e32 v2, 16, v110
	v_and_b32_e32 v3, 0xffff0000, v110
	v_lshlrev_b32_e32 v12, 16, v111
	v_and_b32_e32 v13, 0xffff0000, v111
	s_waitcnt lgkmcnt(0)
	v_pk_mul_f32 v[2:3], v[206:207], v[2:3]
	v_pk_mul_f32 v[10:11], v[208:209], v[12:13]
	v_mul_f32_e32 v3, v3, v3
	v_fmac_f32_e32 v3, v2, v2
	v_mul_f32_e32 v2, v11, v11
	v_fmac_f32_e32 v2, v10, v10
	v_add_f32_e32 v2, v3, v2
	v_add_f32_e32 v1, v1, v2
	s_waitcnt vmcnt(2)
	v_lshlrev_b32_e32 v2, 16, v100
	v_and_b32_e32 v3, 0xffff0000, v100
	v_lshlrev_b32_e32 v12, 16, v101
	v_and_b32_e32 v13, 0xffff0000, v101
	s_waitcnt lgkmcnt(0)
	v_pk_mul_f32 v[2:3], v[102:103], v[2:3]
	v_pk_mul_f32 v[10:11], v[104:105], v[12:13]
	v_mul_f32_e32 v3, v3, v3
	v_fmac_f32_e32 v3, v2, v2
	v_mul_f32_e32 v2, v11, v11
	v_fmac_f32_e32 v2, v10, v10
	v_add_f32_e32 v2, v3, v2
	v_and_b32_e32 v3, 64, v200
	v_add_f32_e32 v2, v1, v2
	v_xor_b32_e32 v1, 16, v200
	v_add_u32_e32 v3, 64, v3
	v_cmp_lt_i32_e32 vcc, v1, v3
	v_mov_b32_e32 v95, v0
	v_readlane_b32 s2, v251, 34
	v_cndmask_b32_e32 v1, v200, v1, vcc
	v_lshlrev_b32_e32 v1, 2, v1
	v_mov_b32_e32 v8, v2
	s_nop 1
	v_permlane16_swap_b32_e32 v2, v8
	v_readlane_b32 s3, v251, 35
	v_mov_b32_e32 v75, v0
	v_add_f32_e32 v225, v2, v8
	v_xor_b32_e32 v2, 32, v200
	v_cmp_lt_i32_e32 vcc, v2, v3
	s_nop 1
	v_cndmask_b32_e32 v2, v200, v2, vcc
	v_lshlrev_b32_e32 v73, 2, v2
	v_lshl_or_b32 v2, s81, 6, v141
	v_sub_u32_e32 v3, 0x3fff, v2
	v_cndmask_b32_e64 v2, v3, v2, s[70:71]
	v_or_b32_e32 v94, s38, v2
	v_lshlrev_b64 v[2:3], 10, v[94:95]
	v_lshl_add_u64 v[102:103], s[2:3], 0, v[2:3]
	v_lshl_add_u64 v[8:9], s[20:21], 1, v[102:103]
	v_lshl_add_u64 v[8:9], v[8:9], 0, v[74:75]
	global_load_dwordx4 v[20:23], v[8:9], off
	global_load_dwordx4 v[16:19], v[8:9], off offset:64
	global_load_dwordx4 v[12:15], v[8:9], off offset:256
	s_nop 0
	global_load_dwordx4 v[8:11], v[8:9], off offset:320
	v_mov_b32_e32 v226, v225
	s_nop 1
	v_permlane32_swap_b32_e32 v225, v226
	s_and_saveexec_b64 s[22:23], s[40:41]
	s_cbranch_execz .LBB0_100
	v_lshl_add_u64 v[4:5], v[102:103], 0, v[74:75]
	global_load_dwordx4 v[4:7], v[4:5], off offset:832

; #define LAS __attribute__((address_space(3)))
; __device__ __forceinline__ f32x4 sigm4(f32x4 x) { return (f32x4){sigm(x[0]), sigm(x[1]), sigm(x[2]), sigm(x[3])}; }
; template <int CTRL> __device__ __forceinline__ float dpp0(float x) { return __builtin_bit_cast(float, __builtin_amdgcn_update_dpp(0, __builtin_bit_cast(int, x), CTRL, 0xf, 0xf, true)); }
; __device__ __forceinline__ float row16_scan(float x) { x += dpp0<0x111>(x); x += dpp0<0x112>(x); x += dpp0<0x114>(x); x += dpp0<0x118>(x); return x; }
; __device__ __forceinline__ void rw_scan(LAS unsigned char* L, const bf16_t* Rg, const bf16_t* Kg, const bf16_t* Vg, const bf16_t* VF, const bf16_t* LO, const bf16_t* wlbT, const bf16_t* albT, const bf16_t* vlbT, ...
;     ...
;                 float bs = 0.f;
; #pragma unroll
;                 for (int tl = 0; tl < 2; ++tl) { const int td = 2 * half + tl; const int c4 = td * 16 + 4 * fq;
;                     const f32x4 lw = sigm4(*(const LAS f32x4*)(CSTb + c4) + accw[tl]) * (-0.6065306597126334f * 1.4426950408889634f);
;                     f32x4 cl;
; #pragma unroll
;                     for (int r = 0; r < 4; ++r) cl[r] = row16_scan(lw[r]);
;                     const f32x4 ep = (f32x4){__builtin_amdgcn_exp2f(cl[0]), __builtin_amdgcn_exp2f(cl[1]), __builtin_amdgcn_exp2f(cl[2]), __builtin_amdgcn_exp2f(cl[3])};
;                     f32x4 epL, em, en;
; #pragma unroll
;                     for (int r = 0; r < 4; ++r) { epL[r] = __shfl(ep[r], (lane & 48) | 15); const float sh = dpp0<0x111>(ep[r]); em[r] = (fr == 0) ? 1.f : sh; en[r] = __builtin_amdgcn_rcpf(ep[r]); }
;                     const f32x4 eL = epL * en;
;                     const f32x4 a4 = sigm4(*(const LAS f32x4*)(CSTb + 128 + c4) + acca[tl]);
;                     const f32x4 kr = tl ? krs1 : krs0; const f32x4 kk4 = kr * *(const LAS f32x4*)(CSTb + 192 + c4) * inv;
;                     const f32x4 kd4 = kr * (1.f + (a4 - 1.f) * *(const LAS f32x4*)(CSTb + 256 + c4)); const f32x4 b4 = kk4 * a4; const f32x4 r4 = tl ? r4s1 : r4s0;
;                     if (ti == q) { const f32x4 rk = r4 * kd4 * *(const LAS f32x4*)(CSTb + 320 + c4); bs += (rk[0] + rk[1]) + (rk[2] + rk[3]); }
.LBB0_103:
	s_or_b64 exec, exec, s[22:23]
	v_cndmask_b32_e64 v2, v111, v107, s[46:47]
	v_cndmask_b32_e64 v3, v110, v106, s[46:47]
	v_lshlrev_b32_e32 v124, 16, v2
	v_and_b32_e32 v125, 0xffff0000, v2
	v_and_or_b32 v2, v200, 64, v64
	s_waitcnt lgkmcnt(1)
	v_pk_add_f32 v[56:57], v[56:57], v[126:127]
	v_lshlrev_b32_e32 v110, 16, v3
	v_and_b32_e32 v111, 0xffff0000, v3
	v_lshl_or_b32 v3, v2, 2, 60
	v_mul_f32_e32 v2, 0xbfb8aa3b, v56
	v_exp_f32_e32 v2, v2
	v_mul_f32_e32 v56, 0xbfb8aa3b, v57
	v_exp_f32_e32 v75, v56
	v_pk_add_f32 v[56:57], v[58:59], v[128:129]
	v_add_f32_e32 v2, 1.0, v2
	v_rcp_f32_e32 v2, v2
	v_mul_f32_e32 v56, 0xbfb8aa3b, v56
	v_exp_f32_e32 v56, v56
	v_add_f32_e32 v58, 1.0, v75
	v_mul_f32_e32 v57, 0xbfb8aa3b, v57
	v_rcp_f32_e32 v58, v58
	v_exp_f32_e32 v57, v57
	v_mul_f32_e32 v59, 0xbf60028a, v2
	v_add_f32_e32 v56, 1.0, v56
	v_rcp_f32_e32 v56, v56
	v_mov_b32_dpp v59, v59 row_shr:1 row_mask:0xf bank_mask:0xf bound_ctrl:1
	v_fmac_f32_e32 v59, 0xbf60028a, v2
	v_add_f32_e32 v57, 1.0, v57
	v_rcp_f32_e32 v57, v57
	v_add_f32_dpp v2, v59, v59 row_shr:2 row_mask:0xf bank_mask:0xf bound_ctrl:1
	v_mul_f32_e32 v59, 0xbf60028a, v58
	s_waitcnt lgkmcnt(0)
	v_pk_add_f32 v[52:53], v[52:53], v[130:131]
	v_add_f32_dpp v2, v2, v2 row_shr:4 row_mask:0xf bank_mask:0xf bound_ctrl:1
	v_mov_b32_dpp v59, v59 row_shr:1 row_mask:0xf bank_mask:0xf bound_ctrl:1
	v_fmac_f32_e32 v59, 0xbf60028a, v58
	v_mul_f32_e32 v52, 0xbfb8aa3b, v52
	v_add_f32_dpp v2, v2, v2 row_shr:8 row_mask:0xf bank_mask:0xf bound_ctrl:1
	v_add_f32_dpp v58, v59, v59 row_shr:2 row_mask:0xf bank_mask:0xf bound_ctrl:1
	v_mul_f32_e32 v59, 0xbf60028a, v56
	v_exp_f32_e32 v126, v2
	v_add_f32_dpp v58, v58, v58 row_shr:4 row_mask:0xf bank_mask:0xf bound_ctrl:1
	v_mov_b32_dpp v59, v59 row_shr:1 row_mask:0xf bank_mask:0xf bound_ctrl:1
	v_fmac_f32_e32 v59, 0xbf60028a, v56
	v_add_f32_dpp v58, v58, v58 row_shr:8 row_mask:0xf bank_mask:0xf bound_ctrl:1
	v_exp_f32_e32 v127, v58
	v_add_f32_dpp v56, v59, v59 row_shr:2 row_mask:0xf bank_mask:0xf bound_ctrl:1
	v_mul_f32_e32 v59, 0xbf60028a, v57
	v_lshlrev_b32_e32 v106, 16, v108
	v_add_f32_dpp v56, v56, v56 row_shr:4 row_mask:0xf bank_mask:0xf bound_ctrl:1
	v_mov_b32_dpp v59, v59 row_shr:1 row_mask:0xf bank_mask:0xf bound_ctrl:1
	v_fmac_f32_e32 v59, 0xbf60028a, v57
	v_add_f32_dpp v56, v56, v56 row_shr:8 row_mask:0xf bank_mask:0xf bound_ctrl:1
	v_exp_f32_e32 v128, v56
	v_add_f32_dpp v57, v59, v59 row_shr:2 row_mask:0xf bank_mask:0xf bound_ctrl:1
	v_exp_f32_e32 v59, v52
	v_mul_f32_e32 v52, 0xbfb8aa3b, v53
	v_exp_f32_e32 v75, v52
	v_pk_add_f32 v[52:53], v[54:55], v[132:133]
	v_add_f32_dpp v57, v57, v57 row_shr:4 row_mask:0xf bank_mask:0xf bound_ctrl:1
	v_mul_f32_e32 v52, 0xbfb8aa3b, v52
	v_exp_f32_e32 v52, v52
	v_mul_f32_e32 v53, 0xbfb8aa3b, v53
	v_exp_f32_e32 v53, v53
	v_add_f32_dpp v57, v57, v57 row_shr:8 row_mask:0xf bank_mask:0xf bound_ctrl:1
	v_exp_f32_e32 v129, v57
	v_add_f32_e32 v54, 1.0, v59
	v_add_f32_e32 v52, 1.0, v52
	v_rcp_f32_e32 v134, v54
	v_add_f32_e32 v54, 1.0, v75
	v_rcp_f32_e32 v136, v52
	v_add_f32_e32 v52, 1.0, v53
	v_rcp_f32_e32 v135, v54
	v_rcp_f32_e32 v137, v52
	ds_read_b128 v[52:55], v69 offset:24320
	ds_read_b128 v[130:133], v69 offset:24576
	ds_bpermute_b32 v56, v3, v126
	ds_bpermute_b32 v57, v3, v127
	ds_bpermute_b32 v58, v3, v128
	ds_bpermute_b32 v59, v3, v129
	v_pk_add_f32 v[198:199], v[136:137], -1.0 op_sel_hi:[1,0]
	v_pk_add_f32 v[202:203], v[134:135], -1.0 op_sel_hi:[1,0]
	s_waitcnt lgkmcnt(4)
	v_pk_fma_f32 v[132:133], v[132:133], v[198:199], 1.0 op_sel_hi:[1,1,0]
	v_pk_fma_f32 v[198:199], v[130:131], v[202:203], 1.0 op_sel_hi:[1,1,0]
	v_and_b32_e32 v107, 0xffff0000, v108
	v_lshlrev_b32_e32 v108, 16, v109
	v_and_b32_e32 v109, 0xffff0000, v109
	v_mov_b32_dpp v2, v126 row_shr:1 row_mask:0xf bank_mask:0xf bound_ctrl:1
	v_mov_b32_dpp v228, v127 row_shr:1 row_mask:0xf bank_mask:0xf bound_ctrl:1
	v_mov_b32_dpp v227, v128 row_shr:1 row_mask:0xf bank_mask:0xf bound_ctrl:1
	v_mov_b32_dpp v229, v129 row_shr:1 row_mask:0xf bank_mask:0xf bound_ctrl:1
	v_pk_mul_f32 v[130:131], v[132:133], v[124:125]
	v_pk_mul_f32 v[132:133], v[198:199], v[110:111]
	v_mov_b32_e32 v75, 0
	s_and_saveexec_b64 s[22:23], s[72:73]
	s_cbranch_execz .LBB0_105
	ds_read_b128 v[206:209], v69 offset:24832
	v_pk_mul_f32 v[198:199], v[130:131], v[108:109]
	v_pk_mul_f32 v[202:203], v[132:133], v[106:107]
	s_waitcnt lgkmcnt(0)
	v_pk_mul_f32 v[198:199], v[198:199], v[208:209]
	v_pk_mul_f32 v[202:203], v[202:203], v[206:207]
	s_nop 0
	v_pk_mov_b32 v[204:205], v[202:203], v[198:199] op_sel:[1,0]
	v_mov_b32_e32 v203, v199
	v_pk_add_f32 v[198:199], v[204:205], v[202:203]
	s_nop 0
	v_add_f32_e32 v75, v198, v199
	v_add_f32_e32 v75, 0, v75

; #define LAS __attribute__((address_space(3)))
; __device__ __forceinline__ unsigned cvt_pk_bf16(float lo, float hi) { const f32x2_t v = {lo, hi}; const bf16x2_t b = __builtin_convertvector(v, bf16x2_t); return __builtin_bit_cast(unsigned, b); }
; __device__ __forceinline__ u32x2 pk4(f32x4 x) { u32x2 w; w.x = cvt_pk_bf16(x[0], x[1]); w.y = cvt_pk_bf16(x[2], x[3]); return w; }
; __device__ __forceinline__ void rw_scan(LAS unsigned char* L, const bf16_t* Rg, const bf16_t* Kg, const bf16_t* Vg, const bf16_t* VF, const bf16_t* LO, const bf16_t* wlbT, const bf16_t* albT, const bf16_t* vlbT, ...
;     ...
;                     const int p4 = 32 * (td >> 1) + 8 * fq + 4 * (td & 1);
;                     *(LAS u32x2*)(KQ + irow * 72 + p4) = pk4(kk4 * em); *(LAS u32x2*)(RQ + irow * 72 + p4) = pk4(r4 * ep);
;                     *(LAS u32x2*)(BD + irow * 72 + p4) = pk4(b4 * en); *(LAS u32x2*)(KD + irow * 72 + p4) = pk4(kd4 * en);
;                     const f32x4 bl = b4 * eL, kl = kd4 * eL;
; #pragma unroll
;                     for (int r = 0; r < 4; ++r) *(LAS unsigned*)(W2 + (c4 + r) * 136 + ti * 32 + 8 * (fr >> 2) + 2 * (fr & 3)) = cvt_pk_bf16(bl[r], kl[r]);
;                     if (fr == 15) *(LAS f32x4*)(LLs + ti * 64 + c4) = epL;
;                 }
;                 if (ti == q) { bs += __shfl_xor(bs, 16); bs += __shfl_xor(bs, 32);
;                     if (fq == 0) BON2[((size_t)(g * 2 + half) * T_ + rowcur) * 16 + h] = bs; }
.LBB0_109:
	s_or_b64 exec, exec, s[22:23]
	v_mov_b32_e32 v3, v2
	v_pk_mul_f32 v[46:47], v[46:47], v[58:59]
	v_pk_mul_f32 v[44:45], v[44:45], v[56:57]
	v_mov_b32_e32 v56, v2
	v_mov_b32_e32 v57, v2
	v_cndmask_b32_e64 v128, v125, 1.0, s[58:59]
	v_rcp_f32_e32 v130, v96
	v_cndmask_b32_e64 v129, v126, 1.0, s[58:59]
	v_rcp_f32_e32 v131, v97
	v_rcp_f32_e32 v132, v98
	v_rcp_f32_e32 v133, v99
	v_cndmask_b32_e64 v124, v124, 1.0, s[58:59]
	v_cndmask_b32_e64 v125, v127, 1.0, s[58:59]
	v_pk_mul_f32 v[46:47], v[56:57], v[46:47]
	v_pk_mul_f32 v[2:3], v[2:3], v[44:45]
	v_pk_mul_f32 v[44:45], v[46:47], v[110:111]
	v_pk_mul_f32 v[56:57], v[2:3], v[108:109]
	v_pk_mul_f32 v[46:47], v[124:125], v[46:47]
	v_pk_mul_f32 v[2:3], v[128:129], v[2:3]
	v_pk_mul_f32 v[52:53], v[96:97], v[52:53]
	v_cvt_pk_bf16_f32 v2, v2, v3
	v_cvt_pk_bf16_f32 v3, v46, v47
	v_pk_mul_f32 v[46:47], v[98:99], v[54:55]
	v_cvt_pk_bf16_f32 v52, v52, v53
	v_cvt_pk_bf16_f32 v53, v46, v47
	v_add_u32_e32 v54, 8, v145
	ds_write2st64_b64 v54, v[2:3], v[52:53] offset0:104 offset1:122
	v_pk_mul_f32 v[2:3], v[132:133], v[44:45]
	v_pk_mul_f32 v[46:47], v[130:131], v[56:57]
	v_pk_mul_f32 v[52:53], v[130:131], v[106:107]
	v_cvt_pk_bf16_f32 v46, v46, v47
	v_cvt_pk_bf16_f32 v47, v2, v3
	v_pk_mul_f32 v[2:3], v[132:133], v[100:101]
	s_waitcnt lgkmcnt(3)
	v_pk_mul_f32 v[126:127], v[130:131], v[48:49]
	s_waitcnt lgkmcnt(1)
	v_pk_mul_f32 v[134:135], v[132:133], v[50:51]
	v_cvt_pk_bf16_f32 v52, v52, v53
	v_cvt_pk_bf16_f32 v53, v2, v3
	ds_write2st64_b64 v54, v[46:47], v[52:53] offset0:49 offset1:67
	v_pk_mul_f32 v[2:3], v[134:135], v[44:45]
	v_pk_mul_f32 v[44:45], v[126:127], v[56:57]
	v_pk_mul_f32 v[52:53], v[126:127], v[106:107]
	v_pk_mul_f32 v[46:47], v[134:135], v[100:101]
	v_cvt_pk_bf16_f32 v44, v44, v52
	v_cvt_pk_bf16_f32 v45, v45, v53
	v_add_u32_e32 v52, 0x1000, v195
	ds_write2_b32 v52, v44, v45 offset0:64 offset1:132
	v_cvt_pk_bf16_f32 v2, v2, v46
	v_cvt_pk_bf16_f32 v3, v3, v47
	v_add_u32_e32 v44, 0x1200, v195
	ds_write2_b32 v44, v2, v3 offset0:72 offset1:140
	s_and_saveexec_b64 s[22:23], s[60:61]
	ds_write_b128 v175, v[48:51] offset:64
	s_or_b64 exec, exec, s[22:23]
	s_and_saveexec_b64 s[22:23], s[72:73]
	s_cbranch_execz .LBB0_114
	v_mov_b32_e32 v1, v75
	s_nop 1
	v_permlane16_swap_b32_e32 v75, v1
	v_add_f32_e32 v1, v75, v1
	v_mov_b32_e32 v2, v1
	s_nop 1
	v_permlane32_swap_b32_e32 v1, v2
	s_and_b64 exec, exec, s[48:49]
	s_cbranch_execz .LBB0_114
	v_lshlrev_b64 v[44:45], 6, v[88:89]
	v_lshl_add_u64 v[44:45], v[82:83], 0, v[44:45]
	s_waitcnt lgkmcnt(0)
	v_add_f32_e32 v1, v1, v2
	global_store_dword v[44:45], v1, off

; #define LAS __attribute__((address_space(3)))
; __device__ __forceinline__ void rw_scan(LAS unsigned char* L, const bf16_t* Rg, const bf16_t* Kg, const bf16_t* Vg, const bf16_t* VF, const bf16_t* LO, const bf16_t* wlbT, const bf16_t* albT, const bf16_t* vlbT, ...
;     ...
;             if (m < 256) { const int sc = wid >> 1;
; #pragma unroll
;                 for (int ml = 0; ml < 3; ++ml) { const int mat = (wid & 1) ? ml + 1 : 0; if ((wid & 1) == 0 && ml > 0) break;     const LAS bf16_t* Am = (mat < 2) ? KQ : RQ; const LAS bf16_t* Bm = (mat & 1) ? KD : BD;
;                     f32x4 acc = {0.f, 0.f, 0.f, 0.f};
;                     acc = mma16(lfrag(Am, 72, sc * 16 + fr, 8 * fq), lfrag(Bm, 72, sc * 16 + fr, 8 * fq), acc);
;                     acc = mma16(lfrag(Am, 72, sc * 16 + fr, 32 + 8 * fq), lfrag(Bm, 72, sc * 16 + fr, 32 + 8 * fq), acc);
; #pragma unroll
;                     for (int r = 0; r < 4; ++r) { const int t = 4 * fq + r, sidx = fr; const bool keep = (mat < 2) ? (sidx < t) : (sidx <= t); const float val = keep ? acc[r] : 0.f;
;                         if (mat == 0) MM[(sc * 16 + t) * 20 + sidx] = val;
;                         else if (mat == 1) NA[(sc * 16 + t) * 32 + 8 * (sidx >> 2) + 4 + (sidx & 3)] = f2bf(val);
;                         else if (mat == 2) AR[(sc * 16 + t) * 40 + 8 * (sidx >> 2) + 2 * (sidx & 3)] = f2bf(val);
;                         else AR[(sc * 16 + t) * 40 + 8 * (sidx >> 2) + 2 * (sidx & 3) + 1] = f2bf(val); } }
;                 if ((wid & 1) == 0) { asm volatile("" ::: "memory");
;                     const int c = lane & 15; float tcol[16];
; #pragma unroll
;                     for (int i = 0; i < 16; ++i) { float acc0 = (i == c) ? 1.f : 0.f, acc1 = 0.f;
; #pragma unroll
;                         for (int j4 = 0; j4 < 4; ++j4) { if (j4 * 4 < i) { const f32x4 m4 = *(const LAS f32x4*)(MM + (sc * 16 + i) * 20 + j4 * 4);
; #pragma unroll
;                                 for (int jr = 0; jr < 4; ++jr) { const int j = j4 * 4 + jr; if (j < i) { if (jr & 1) acc1 -= m4[jr] * tcol[j]; else acc0 -= m4[jr] * tcol[j]; } } } }
;                         tcol[i] = acc0 + acc1; }
;                     if (lane < 16) {
; #pragma unroll
;                         for (int i = 0; i < 16; ++i) TI[(sc * 16 + i) * 32 + 8 * (c >> 2) + (c & 3)] = f2bf(-tcol[i]); } }
.LBB0_123:
	s_waitcnt lgkmcnt(0)
	s_barrier
	v_cndmask_b32_e64 v1, 0, 1, s[24:25]
	v_cmp_ne_u32_e64 s[74:75], 1, v1
	s_andn2_b64 vcc, exec, s[24:25]
	s_cbranch_vccnz .LBB0_147
	s_and_b64 vcc, exec, s[50:51]
	s_cbranch_vccnz .Lp2_odd_h1
	ds_read_b128 v[212:215], v156 offset:53248
	ds_read_b128 v[216:219], v146
	ds_read_b128 v[230:233], v156 offset:53312
	ds_read_b128 v[234:237], v146 offset:64
	s_waitcnt lgkmcnt(2)
	v_mfma_f32_16x16x32_bf16 v[40:43], v[212:215], v[216:219], 0
	s_waitcnt lgkmcnt(0)
	v_mfma_f32_16x16x32_bf16 v[40:43], v[230:233], v[234:237], v[40:43]
	s_and_saveexec_b64 s[26:27], s[48:49]
	s_nop 7
	v_readlane_b32 s2, v41, 0
	v_readlane_b32 s3, v42, 0
	v_readlane_b32 s4, v42, 1
	v_readlane_b32 s5, v43, 0
	v_readlane_b32 s6, v43, 1
	v_fma_f32 v44, -s2, v157, v158
	v_cvt_pk_bf16_f32 v1, -v44, v44
	ds_write_b16 v178, v1 offset:64
	v_readlane_b32 s7, v43, 2
	v_fma_f32 v45, -s3, v157, v160
	v_readlane_b32 s8, v40, 16
	v_fma_f32 v59, -s4, v44, 0
	v_add_f32_e32 v45, v45, v59
	v_cvt_pk_bf16_f32 v1, -v45, v45
	ds_write_b16 v178, v1 offset:128
	v_readlane_b32 s9, v40, 17
	v_fma_f32 v46, -s5, v157, v161
	v_readlane_b32 s10, v40, 18
	v_fma_f32 v73, -s6, v44, 0
	v_readlane_b32 s11, v40, 19
	v_fma_f32 v46, -s7, v45, v46
	v_add_f32_e32 v46, v46, v73
	v_cvt_pk_bf16_f32 v1, -v46, v46
	ds_write_b16 v178, v1 offset:192
	v_readlane_b32 s14, v41, 16
	v_fma_f32 v47, -s8, v157, v162
	v_readlane_b32 s98, v41, 17
	v_fma_f32 v59, -s9, v44, 0
	v_readlane_b32 s99, v41, 18
	v_fma_f32 v47, -s10, v45, v47
	v_readlane_b32 s2, v41, 19
	v_fma_f32 v59, -s11, v46, v59
	v_add_f32_e32 v47, v47, v59
	v_cvt_pk_bf16_f32 v1, -v47, v47
	ds_write_b16 v178, v1 offset:256
	v_readlane_b32 s3, v41, 20
	v_fma_f32 v48, -s14, v157, v163
	v_readlane_b32 s4, v42, 16
	v_fma_f32 v73, -s98, v44, 0
	v_readlane_b32 s5, v42, 17
	v_fma_f32 v48, -s99, v45, v48
	v_readlane_b32 s6, v42, 18
	v_fma_f32 v73, -s2, v46, v73
	v_readlane_b32 s7, v42, 19
	v_fma_f32 v48, -s3, v47, v48
	v_add_f32_e32 v48, v48, v73
	v_cvt_pk_bf16_f32 v1, -v48, v48
	ds_write_b16 v178, v1 offset:320
	v_readlane_b32 s8, v42, 20
	v_fma_f32 v49, -s4, v157, v164
	v_readlane_b32 s9, v42, 21
	v_fma_f32 v59, -s5, v44, 0
	v_readlane_b32 s10, v43, 16
	v_fma_f32 v49, -s6, v45, v49
	v_readlane_b32 s11, v43, 17
	v_fma_f32 v59, -s7, v46, v59
	v_readlane_b32 s14, v43, 18
	v_fma_f32 v49, -s8, v47, v49
	v_readlane_b32 s98, v43, 19
	v_fma_f32 v59, -s9, v48, v59
	v_add_f32_e32 v49, v49, v59
	v_cvt_pk_bf16_f32 v1, -v49, v49
	ds_write_b16 v178, v1 offset:384
	v_readlane_b32 s99, v43, 20
	v_fma_f32 v50, -s10, v157, v165
	v_readlane_b32 s2, v43, 21
	v_fma_f32 v73, -s11, v44, 0
	v_readlane_b32 s3, v43, 22
	v_fma_f32 v50, -s14, v45, v50
	v_readlane_b32 s4, v40, 32
	v_fma_f32 v73, -s98, v46, v73
	v_readlane_b32 s5, v40, 33
	v_fma_f32 v50, -s99, v47, v50
	v_readlane_b32 s6, v40, 34
	v_fma_f32 v73, -s2, v48, v73
	v_readlane_b32 s7, v40, 35
	v_fma_f32 v50, -s3, v49, v50
	v_add_f32_e32 v50, v50, v73
	v_cvt_pk_bf16_f32 v1, -v50, v50
	ds_write_b16 v178, v1 offset:448
	v_readlane_b32 s8, v40, 36
	v_fma_f32 v51, -s4, v157, v166
	v_readlane_b32 s9, v40, 37
	v_fma_f32 v59, -s5, v44, 0
	v_readlane_b32 s10, v40, 38
	v_fma_f32 v51, -s6, v45, v51
	v_readlane_b32 s11, v40, 39
	v_fma_f32 v59, -s7, v46, v59
	v_readlane_b32 s14, v41, 32
	v_fma_f32 v51, -s8, v47, v51
	v_readlane_b32 s98, v41, 33
	v_fma_f32 v59, -s9, v48, v59
	v_readlane_b32 s99, v41, 34
	v_fma_f32 v51, -s10, v49, v51
	v_readlane_b32 s2, v41, 35
	v_fma_f32 v59, -s11, v50, v59
	v_add_f32_e32 v51, v51, v59
	v_cvt_pk_bf16_f32 v1, -v51, v51
	ds_write_b16 v178, v1 offset:512
	v_readlane_b32 s3, v41, 36
	v_fma_f32 v52, -s14, v157, v167
	v_readlane_b32 s4, v41, 37
	v_fma_f32 v73, -s98, v44, 0
	v_readlane_b32 s5, v41, 38
	v_fma_f32 v52, -s99, v45, v52
	v_readlane_b32 s6, v41, 39
	v_fma_f32 v73, -s2, v46, v73
	v_readlane_b32 s7, v41, 40
	v_fma_f32 v52, -s3, v47, v52
	v_readlane_b32 s8, v42, 32
	v_fma_f32 v73, -s4, v48, v73
	v_readlane_b32 s9, v42, 33
	v_fma_f32 v52, -s5, v49, v52
	v_readlane_b32 s10, v42, 34
	v_fma_f32 v73, -s6, v50, v73
	v_readlane_b32 s11, v42, 35
	v_fma_f32 v52, -s7, v51, v52
	v_add_f32_e32 v52, v52, v73
	v_cvt_pk_bf16_f32 v1, -v52, v52
	ds_write_b16 v178, v1 offset:576
	v_readlane_b32 s14, v42, 36
	v_fma_f32 v53, -s8, v157, v168
	v_readlane_b32 s98, v42, 37
	v_fma_f32 v59, -s9, v44, 0
	v_readlane_b32 s99, v42, 38
	v_fma_f32 v53, -s10, v45, v53
	v_readlane_b32 s2, v42, 39
	v_fma_f32 v59, -s11, v46, v59
	v_readlane_b32 s3, v42, 40
	v_fma_f32 v53, -s14, v47, v53
	v_readlane_b32 s4, v42, 41
	v_fma_f32 v59, -s98, v48, v59
	v_readlane_b32 s5, v43, 32
	v_fma_f32 v53, -s99, v49, v53
	v_readlane_b32 s6, v43, 33
	v_fma_f32 v59, -s2, v50, v59
	v_readlane_b32 s7, v43, 34
	v_fma_f32 v53, -s3, v51, v53
	v_readlane_b32 s8, v43, 35
	v_fma_f32 v59, -s4, v52, v59
	v_add_f32_e32 v53, v53, v59
	v_cvt_pk_bf16_f32 v1, -v53, v53
	ds_write_b16 v178, v1 offset:640
	v_readlane_b32 s9, v43, 36
	v_fma_f32 v54, -s5, v157, v169
	v_readlane_b32 s10, v43, 37
	v_fma_f32 v73, -s6, v44, 0
	v_readlane_b32 s11, v43, 38
	v_fma_f32 v54, -s7, v45, v54
	v_readlane_b32 s14, v43, 39
	v_fma_f32 v73, -s8, v46, v73
	v_readlane_b32 s98, v43, 40
	v_fma_f32 v54, -s9, v47, v54
	v_readlane_b32 s99, v43, 41
	v_fma_f32 v73, -s10, v48, v73
	v_readlane_b32 s2, v43, 42
	v_fma_f32 v54, -s11, v49, v54
	v_readlane_b32 s3, v40, 48
	v_fma_f32 v73, -s14, v50, v73
	v_readlane_b32 s4, v40, 49
	v_fma_f32 v54, -s98, v51, v54
	v_readlane_b32 s5, v40, 50
	v_fma_f32 v73, -s99, v52, v73
	v_readlane_b32 s6, v40, 51
	v_fma_f32 v54, -s2, v53, v54
	v_add_f32_e32 v54, v54, v73
	v_cvt_pk_bf16_f32 v1, -v54, v54
	ds_write_b16 v178, v1 offset:704
; #define LAS __attribute__((address_space(3)))
; __device__ __forceinline__ bf16_t f2bf(float f) { return (bf16_t)(cvt_pk_bf16(f, 0.f) & 0xffffu); }
; __device__ __forceinline__ f32x4 mma16(bf16x8 a, bf16x8 b, f32x4 c) { return __builtin_amdgcn_mfma_f32_16x16x32_bf16(a, b, c, 0, 0, 0); }
; __device__ __forceinline__ void rw_scan(LAS unsigned char* L, const bf16_t* Rg, const bf16_t* Kg, const bf16_t* Vg, const bf16_t* VF, const bf16_t* LO, const bf16_t* wlbT, const bf16_t* albT, const bf16_t* vlbT, ...
;     ...
;                 for (int ml = 0; ml < 3; ++ml) { const int mat = (wid & 1) ? ml + 1 : 0; if ((wid & 1) == 0 && ml > 0) break;     const LAS bf16_t* Am = (mat < 2) ? KQ : RQ; const LAS bf16_t* Bm = (mat & 1) ? KD : BD;
;                     f32x4 acc = {0.f, 0.f, 0.f, 0.f};
;                     acc = mma16(lfrag(Am, 72, sc * 16 + fr, 8 * fq), lfrag(Bm, 72, sc * 16 + fr, 8 * fq), acc);
;                     acc = mma16(lfrag(Am, 72, sc * 16 + fr, 32 + 8 * fq), lfrag(Bm, 72, sc * 16 + fr, 32 + 8 * fq), acc);
; #pragma unroll
;                     for (int r = 0; r < 4; ++r) { const int t = 4 * fq + r, sidx = fr; const bool keep = (mat < 2) ? (sidx < t) : (sidx <= t); const float val = keep ? acc[r] : 0.f;
;                         if (mat == 0) MM[(sc * 16 + t) * 20 + sidx] = val;
;                         else if (mat == 1) NA[(sc * 16 + t) * 32 + 8 * (sidx >> 2) + 4 + (sidx & 3)] = f2bf(val);
;                         else if (mat == 2) AR[(sc * 16 + t) * 40 + 8 * (sidx >> 2) + 2 * (sidx & 3)] = f2bf(val);
;                         else AR[(sc * 16 + t) * 40 + 8 * (sidx >> 2) + 2 * (sidx & 3) + 1] = f2bf(val); } }
;     ...
;                     for (int i = 0; i < 16; ++i) { float acc0 = (i == c) ? 1.f : 0.f, acc1 = 0.f;
; #pragma unroll
;                         for (int j4 = 0; j4 < 4; ++j4) { if (j4 * 4 < i) { const f32x4 m4 = *(const LAS f32x4*)(MM + (sc * 16 + i) * 20 + j4 * 4);
; #pragma unroll
;                                 for (int jr = 0; jr < 4; ++jr) { const int j = j4 * 4 + jr; if (j < i) { if (jr & 1) acc1 -= m4[jr] * tcol[j]; else acc0 -= m4[jr] * tcol[j]; } } } }
;                         tcol[i] = acc0 + acc1; }
;                     if (lane < 16) {
; #pragma unroll
;                         for (int i = 0; i < 16; ++i) TI[(sc * 16 + i) * 32 + 8 * (c >> 2) + (c & 3)] = f2bf(-tcol[i]); } }
	v_readlane_b32 s7, v40, 52
	v_fma_f32 v55, -s3, v157, v170
	v_readlane_b32 s8, v40, 53
	v_fma_f32 v59, -s4, v44, 0
	v_readlane_b32 s9, v40, 54
	v_fma_f32 v55, -s5, v45, v55
	v_readlane_b32 s10, v40, 55
	v_fma_f32 v59, -s6, v46, v59
	v_readlane_b32 s11, v40, 56
	v_fma_f32 v55, -s7, v47, v55
	v_readlane_b32 s14, v40, 57
	v_fma_f32 v59, -s8, v48, v59
	v_readlane_b32 s98, v40, 58
	v_fma_f32 v55, -s9, v49, v55
	v_readlane_b32 s99, v40, 59
	v_fma_f32 v59, -s10, v50, v59
	v_readlane_b32 s2, v41, 48
	v_fma_f32 v55, -s11, v51, v55
	v_readlane_b32 s3, v41, 49
	v_fma_f32 v59, -s14, v52, v59
	v_readlane_b32 s4, v41, 50
	v_fma_f32 v55, -s98, v53, v55
	v_readlane_b32 s5, v41, 51
	v_fma_f32 v59, -s99, v54, v59
	v_add_f32_e32 v55, v55, v59
	v_cvt_pk_bf16_f32 v1, -v55, v55
	ds_write_b16 v178, v1 offset:768
	v_readlane_b32 s6, v41, 52
	v_fma_f32 v56, -s2, v157, v171
	v_readlane_b32 s7, v41, 53
	v_fma_f32 v73, -s3, v44, 0
	v_readlane_b32 s8, v41, 54
	v_fma_f32 v56, -s4, v45, v56
	v_readlane_b32 s9, v41, 55
	v_fma_f32 v73, -s5, v46, v73
	v_readlane_b32 s10, v41, 56
	v_fma_f32 v56, -s6, v47, v56
	v_readlane_b32 s11, v41, 57
	v_fma_f32 v73, -s7, v48, v73
	v_readlane_b32 s14, v41, 58
	v_fma_f32 v56, -s8, v49, v56
	v_readlane_b32 s98, v41, 59
	v_fma_f32 v73, -s9, v50, v73
	v_readlane_b32 s99, v41, 60
	v_fma_f32 v56, -s10, v51, v56
	v_readlane_b32 s2, v42, 48
	v_fma_f32 v73, -s11, v52, v73
	v_readlane_b32 s3, v42, 49
	v_fma_f32 v56, -s14, v53, v56
	v_readlane_b32 s4, v42, 50
	v_fma_f32 v73, -s98, v54, v73
	v_readlane_b32 s5, v42, 51
	v_fma_f32 v56, -s99, v55, v56
	v_add_f32_e32 v56, v56, v73
	v_cvt_pk_bf16_f32 v1, -v56, v56
	ds_write_b16 v178, v1 offset:832
	v_readlane_b32 s6, v42, 52
	v_fma_f32 v57, -s2, v157, v172
	v_readlane_b32 s7, v42, 53
	v_fma_f32 v59, -s3, v44, 0
	v_readlane_b32 s8, v42, 54
	v_fma_f32 v57, -s4, v45, v57
	v_readlane_b32 s9, v42, 55
	v_fma_f32 v59, -s5, v46, v59
	v_readlane_b32 s10, v42, 56
	v_fma_f32 v57, -s6, v47, v57
	v_readlane_b32 s11, v42, 57
	v_fma_f32 v59, -s7, v48, v59
	v_readlane_b32 s14, v42, 58
	v_fma_f32 v57, -s8, v49, v57
	v_readlane_b32 s98, v42, 59
	v_fma_f32 v59, -s9, v50, v59
	v_readlane_b32 s99, v42, 60
	v_fma_f32 v57, -s10, v51, v57
	v_readlane_b32 s2, v42, 61
	v_fma_f32 v59, -s11, v52, v59
	v_readlane_b32 s3, v43, 48
	v_fma_f32 v57, -s14, v53, v57
	v_readlane_b32 s4, v43, 49
	v_fma_f32 v59, -s98, v54, v59
	v_readlane_b32 s5, v43, 50
	v_fma_f32 v57, -s99, v55, v57
	v_readlane_b32 s6, v43, 51
	v_fma_f32 v59, -s2, v56, v59
	v_add_f32_e32 v57, v57, v59
	v_cvt_pk_bf16_f32 v1, -v57, v57
	ds_write_b16 v178, v1 offset:896
	v_readlane_b32 s7, v43, 52
	v_fma_f32 v58, -s3, v157, v173
	v_readlane_b32 s8, v43, 53
	v_fma_f32 v73, -s4, v44, 0
	v_readlane_b32 s9, v43, 54
	v_fma_f32 v58, -s5, v45, v58
	v_readlane_b32 s10, v43, 55
	v_fma_f32 v73, -s6, v46, v73
	v_readlane_b32 s11, v43, 56
	v_fma_f32 v58, -s7, v47, v58
	v_readlane_b32 s14, v43, 57
	v_fma_f32 v73, -s8, v48, v73
	v_readlane_b32 s98, v43, 58
	v_fma_f32 v58, -s9, v49, v58
	v_readlane_b32 s99, v43, 59
	v_fma_f32 v73, -s10, v50, v73
	v_readlane_b32 s2, v43, 60
	v_fma_f32 v58, -s11, v51, v58
	v_readlane_b32 s3, v43, 61
	v_fma_f32 v73, -s14, v52, v73
	v_readlane_b32 s4, v43, 62
	v_fma_f32 v58, -s98, v53, v58
	v_fma_f32 v73, -s99, v54, v73
	v_fma_f32 v58, -s2, v55, v58
	v_fma_f32 v73, -s3, v56, v73
	v_fma_f32 v58, -s4, v57, v58
	v_add_f32_e32 v58, v58, v73
	v_cvt_pk_bf16_f32 v1, -v58, v58
	ds_write_b16 v178, v1 offset:960
	ds_write_b16 v178, v174
	s_or_b64 exec, exec, s[26:27]
	s_branch .LBB0_147
.Lp2_odd_h1:
	ds_read_b128 v[40:43], v156 offset:53248
	ds_read_b128 v[44:47], v156 offset:34304
	ds_read_b128 v[48:51], v156 offset:62464
	ds_read_b128 v[52:55], v156 offset:25088
	ds_read_b128 v[56:59], v156 offset:53312
	ds_read_b128 v[212:215], v156 offset:34368
	ds_read_b128 v[216:219], v156 offset:62528
	ds_read_b128 v[230:233], v156 offset:25152
	v_add_u32_e32 v2, v176, v148
	v_add_u32_e32 v3, v176, v150
	v_add_u32_e32 v73, v176, v152
	v_add_u32_e32 v75, v176, v155
	s_waitcnt lgkmcnt(6)
	v_mfma_f32_16x16x32_bf16 v[234:237], v[40:43], v[44:47], 0
	s_waitcnt lgkmcnt(4)
	v_mfma_f32_16x16x32_bf16 v[238:241], v[48:51], v[52:55], 0
	v_mfma_f32_16x16x32_bf16 v[246:249], v[48:51], v[44:47], 0
	s_waitcnt lgkmcnt(2)
	v_mfma_f32_16x16x32_bf16 v[234:237], v[56:59], v[212:215], v[234:237]
	s_waitcnt lgkmcnt(0)
	v_mfma_f32_16x16x32_bf16 v[238:241], v[216:219], v[230:233], v[238:241]
	v_mfma_f32_16x16x32_bf16 v[246:249], v[216:219], v[212:215], v[246:249]
	v_add_u32_e32 v44, v177, v147
	v_add_u32_e32 v45, v177, v149
	v_add_u32_e32 v46, v177, v151
	v_add_u32_e32 v47, v177, v153
	s_nop 1
	v_cndmask_b32_e64 v1, 0, v234, s[52:53]
	v_cvt_pk_bf16_f32 v1, v1, v1
	ds_write_b16 v44, v1
	v_cndmask_b32_e64 v1, v235, 0, s[54:55]
	v_cvt_pk_bf16_f32 v1, v1, v1
	ds_write_b16 v45, v1
	v_cndmask_b32_e64 v1, 0, v236, s[56:57]
	v_cvt_pk_bf16_f32 v1, v1, v1
	ds_write_b16 v46, v1
	v_cndmask_b32_e64 v1, 0, v237, s[62:63]
	v_cvt_pk_bf16_f32 v1, v1, v1
	ds_write_b16 v47, v1
	v_cvt_pk_bf16_f32 v1, v238, v238
	v_cndmask_b32_e64 v1, v1, 0, s[54:55]
	ds_write_b16 v2, v1
	v_cvt_pk_bf16_f32 v1, v239, v239
	v_cndmask_b32_e64 v1, v1, 0, s[64:65]
	ds_write_b16 v3, v1
	v_cvt_pk_bf16_f32 v1, v240, v240
	v_cndmask_b32_e64 v1, v1, 0, s[66:67]
	ds_write_b16 v73, v1
	v_cvt_pk_bf16_f32 v1, v241, v241
	v_cndmask_b32_e64 v1, v1, 0, s[68:69]
	ds_write_b16 v75, v1
	v_cvt_pk_bf16_f32 v1, v246, v246
	v_cndmask_b32_e64 v1, v1, 0, s[54:55]
	ds_write_b16 v2, v1 offset:2
	v_cvt_pk_bf16_f32 v1, v247, v247
	v_cndmask_b32_e64 v1, v1, 0, s[64:65]
	ds_write_b16 v3, v1 offset:2
	v_cvt_pk_bf16_f32 v1, v248, v248
	v_cndmask_b32_e64 v1, v1, 0, s[66:67]
	ds_write_b16 v73, v1 offset:2
	v_cvt_pk_bf16_f32 v1, v249, v249
	v_cndmask_b32_e64 v1, v1, 0, s[68:69]
	ds_write_b16 v75, v1 offset:2
	s_branch .LBB0_147
.LBB0_147:
	s_waitcnt lgkmcnt(0)
	s_barrier
	s_or_b32 s26, s81, 1
	s_and_saveexec_b64 s[24:25], s[44:45]
	s_cbranch_execz .LBB0_151
	s_setprio 3
	s_cmpk_eq_i32 s26, 0x101
	s_cbranch_scc1 .LBB0_151
	s_mov_b32 s27, 4
	v_mov_b32_e32 v48, v71
	v_mov_b32_e32 v49, v70
	v_mov_b32_e32 v50, v64
	v_mov_b32_e32 v51, v191
	v_add_u32_e32 v52, 0xd000, v190
	v_mov_b32_e32 v53, v189
	v_mov_b32_e32 v54, v188
	v_mov_b32_e32 v55, v192

; #define LAS __attribute__((address_space(3)))
; __device__ __forceinline__ f32x4 mma16(bf16x8 a, bf16x8 b, f32x4 c) { return __builtin_amdgcn_mfma_f32_16x16x32_bf16(a, b, c, 0, 0, 0); }
; __device__ __forceinline__ f32x4 unpk4(u32x2 w) { return (f32x4){__uint_as_float(w.x << 16), __uint_as_float(w.x & 0xffff0000u), __uint_as_float(w.y << 16), __uint_as_float(w.y & 0xffff0000u)}; }
; __device__ __forceinline__ void rw_scan(LAS unsigned char* L, const bf16_t* Rg, const bf16_t* Kg, const bf16_t* Vg, const bf16_t* VF, const bf16_t* LO, const bf16_t* wlbT, const bf16_t* albT, const bf16_t* vlbT, ...
;     ...
;                 f32x4 accw[2], acca[2], accv = (f32x4){0.f, 0.f, 0.f, 0.f};
; #pragma unroll
;                 for (int tl = 0; tl < 2; ++tl) { const int td = 2 * half + tl; accw[tl] = (f32x4){0.f, 0.f, 0.f, 0.f}; acca[tl] = (f32x4){0.f, 0.f, 0.f, 0.f};
;                     accw[tl] = mma16(lfrag(BTw, 72, td * 16 + fr, 8 * fq), flw0, accw[tl]); accw[tl] = mma16(lfrag(BTw, 72, td * 16 + fr, 32 + 8 * fq), flw1, accw[tl]);
;                     acca[tl] = mma16(lfrag(BTa, 72, td * 16 + fr, 8 * fq), fla0, acca[tl]); acca[tl] = mma16(lfrag(BTa, 72, td * 16 + fr, 32 + 8 * fq), fla1, acca[tl]); }
;                 if (hasvf && hasv) accv = mma16(lfrag(BTv, 40, q * 16 + fr, 8 * fq), flv, accv);
;                 float n2 = 0.f;
; #pragma unroll
;                 for (int td = 0; td < 4; ++td) { const f32x4 kk_ = unpk4(xK[td]) * *(const LAS f32x4*)(CSTb + 192 + td * 16 + 4 * fq); n2 += (kk_[0] * kk_[0] + kk_[1] * kk_[1]) + (kk_[2] * kk_[2] + kk_[3] * kk_[3]); }
;                 n2 += __shfl_xor(n2, 16); n2 += __shfl_xor(n2, 32);
;                 const float inv = fminf(__builtin_amdgcn_rsqf(n2), 1e12f);
;                 const f32x4 krs0 = unpk4(half ? xK[2] : xK[0]), krs1 = unpk4(half ? xK[3] : xK[1]), r4s0 = unpk4(xR[0]), r4s1 = unpk4(xR[1]); const f32x4 v4u = unpk4(xV), vf4u = unpk4(xVF);
;                 asm volatile("" ::: "memory");
;                 if (m + 1 < 256) RW_LOADS(m + 1);
.LBB0_151:
	s_or_b64 exec, exec, s[24:25]
	s_and_b64 vcc, exec, s[74:75]
	s_cbranch_vccnz .LBB0_161
	v_add_u32_e32 v1, v66, v224
	ds_read_b128 v[212:215], v68
	ds_read_b128 v[216:219], v68 offset:64
	ds_read_b128 v[230:233], v68 offset:9216
	ds_read_b128 v[234:237], v68 offset:9280
	ds_read_b128 v[238:241], v68 offset:2304
	ds_read_b128 v[246:249], v68 offset:2368
	ds_read_b128 v[88:91], v68 offset:11520
	ds_read_b128 v[96:99], v68 offset:11584
	ds_read_b128 v[106:109], v66 offset:24320
	ds_read_b128 v[202:205], v66 offset:24384
	ds_read_b128 v[206:209], v66 offset:24448
	ds_read_b128 v[134:137], v66 offset:24512
	ds_read_b128 v[126:129], v69 offset:23552
	ds_read_b128 v[130:133], v69 offset:24064
	s_waitcnt vmcnt(9) lgkmcnt(13)
	v_mfma_f32_16x16x32_bf16 v[40:43], v[212:215], v[20:23], 0
	ds_read_b128 v[212:215], v1 offset:18432
	s_waitcnt vmcnt(8) lgkmcnt(13)
	v_mfma_f32_16x16x32_bf16 v[56:59], v[216:219], v[16:19], v[40:43]
	s_waitcnt vmcnt(7) lgkmcnt(12)
	v_mfma_f32_16x16x32_bf16 v[40:43], v[230:233], v[12:15], 0
	s_waitcnt vmcnt(6) lgkmcnt(11)
	v_mfma_f32_16x16x32_bf16 v[52:55], v[234:237], v[8:11], v[40:43]
	s_waitcnt lgkmcnt(10)
	v_mfma_f32_16x16x32_bf16 v[40:43], v[238:241], v[20:23], 0
	s_waitcnt lgkmcnt(9)
	v_mfma_f32_16x16x32_bf16 v[48:51], v[246:249], v[16:19], v[40:43]
	s_waitcnt lgkmcnt(8)
	v_mfma_f32_16x16x32_bf16 v[40:43], v[88:91], v[12:15], 0
	s_waitcnt lgkmcnt(7)
	v_mfma_f32_16x16x32_bf16 v[44:47], v[96:99], v[8:11], v[40:43]
	s_nop 6
	v_mov_b32_e32 v40, 0
	v_mov_b32_e32 v41, 0
	v_mov_b32_e32 v42, 0
	v_mov_b32_e32 v43, 0
	s_and_saveexec_b64 s[24:25], s[40:41]
	s_cbranch_execz .LBB0_154
	s_waitcnt lgkmcnt(0)
	v_mfma_f32_16x16x32_bf16 v[40:43], v[212:215], v[4:7], 0
.LBB0_154:
	s_or_b64 exec, exec, s[24:25]
	s_waitcnt vmcnt(5)
	v_lshlrev_b32_e32 v2, 16, v120
	v_and_b32_e32 v3, 0xffff0000, v120
	v_lshlrev_b32_e32 v92, 16, v121
	v_and_b32_e32 v93, 0xffff0000, v121
	s_waitcnt lgkmcnt(0)
	v_pk_mul_f32 v[2:3], v[106:107], v[2:3]
	v_pk_mul_f32 v[90:91], v[108:109], v[92:93]
	v_mul_f32_e32 v1, v3, v3
	v_fmac_f32_e32 v1, v2, v2
	v_mul_f32_e32 v2, v91, v91
	v_fmac_f32_e32 v2, v90, v90
	v_add_f32_e32 v1, v1, v2
	s_waitcnt vmcnt(4)
	v_lshlrev_b32_e32 v2, 16, v114
	v_and_b32_e32 v3, 0xffff0000, v114
	v_lshlrev_b32_e32 v92, 16, v115
	v_and_b32_e32 v93, 0xffff0000, v115
	s_waitcnt lgkmcnt(0)
	v_pk_mul_f32 v[2:3], v[202:203], v[2:3]
	v_pk_mul_f32 v[90:91], v[204:205], v[92:93]
	v_mul_f32_e32 v3, v3, v3
	v_fmac_f32_e32 v3, v2, v2
	v_mul_f32_e32 v2, v91, v91
	v_fmac_f32_e32 v2, v90, v90
	v_add_f32_e32 v2, v3, v2
	v_add_f32_e32 v1, v1, v2
	s_waitcnt vmcnt(3)
	v_lshlrev_b32_e32 v2, 16, v122
	v_and_b32_e32 v3, 0xffff0000, v122
	v_lshlrev_b32_e32 v92, 16, v123
	v_and_b32_e32 v93, 0xffff0000, v123
	s_waitcnt lgkmcnt(0)
	v_pk_mul_f32 v[2:3], v[206:207], v[2:3]
	v_pk_mul_f32 v[90:91], v[208:209], v[92:93]
	v_mul_f32_e32 v3, v3, v3
	v_fmac_f32_e32 v3, v2, v2
	v_mul_f32_e32 v2, v91, v91
	v_fmac_f32_e32 v2, v90, v90
	v_add_f32_e32 v2, v3, v2
	v_add_f32_e32 v1, v1, v2
	s_waitcnt vmcnt(2)
	v_lshlrev_b32_e32 v2, 16, v116
	v_and_b32_e32 v3, 0xffff0000, v116
	v_lshlrev_b32_e32 v92, 16, v117
	v_and_b32_e32 v93, 0xffff0000, v117
	s_waitcnt lgkmcnt(0)
	v_pk_mul_f32 v[2:3], v[134:135], v[2:3]
	v_pk_mul_f32 v[90:91], v[136:137], v[92:93]
	v_mul_f32_e32 v3, v3, v3
	v_fmac_f32_e32 v3, v2, v2
	v_mul_f32_e32 v2, v91, v91
	v_fmac_f32_e32 v2, v90, v90
	v_add_f32_e32 v2, v3, v2
	v_and_b32_e32 v3, 64, v200
	v_add_f32_e32 v2, v1, v2
	v_xor_b32_e32 v1, 16, v200
	v_add_u32_e32 v3, 64, v3
	v_cmp_lt_i32_e32 vcc, v1, v3
	s_cmpk_eq_i32 s81, 0xfe
	s_nop 0
	v_cndmask_b32_e32 v1, v200, v1, vcc
	v_lshlrev_b32_e32 v1, 2, v1
	v_mov_b32_e32 v73, v2
	s_nop 1
	v_permlane16_swap_b32_e32 v2, v73
	v_add_f32_e32 v225, v2, v73
	v_xor_b32_e32 v2, 32, v200
	v_cmp_lt_i32_e32 vcc, v2, v3
	s_nop 1
	v_cndmask_b32_e32 v2, v200, v2, vcc
	v_lshlrev_b32_e32 v73, 2, v2
	v_mov_b32_e32 v226, v225
	s_nop 1
	v_permlane32_swap_b32_e32 v225, v226
	s_cbranch_scc1 .LBB0_162
	v_lshl_add_u32 v2, s26, 6, v141
	v_sub_u32_e32 v3, 0x3fff, v2
	v_cndmask_b32_e64 v2, v3, v2, s[70:71]
	v_add_u32_e32 v88, s38, v2
	v_mov_b32_e32 v89, v0
	v_readlane_b32 s2, v251, 34
	v_lshlrev_b64 v[2:3], 10, v[88:89]
	v_readlane_b32 s3, v251, 35
	v_mov_b32_e32 v75, v0
	s_nop 0
	v_lshl_add_u64 v[90:91], s[2:3], 0, v[2:3]
	v_lshl_add_u64 v[8:9], s[20:21], 1, v[90:91]
	v_lshl_add_u64 v[8:9], v[8:9], 0, v[74:75]
	global_load_dwordx4 v[20:23], v[8:9], off
	global_load_dwordx4 v[16:19], v[8:9], off offset:64
	global_load_dwordx4 v[12:15], v[8:9], off offset:256
	s_nop 0
	global_load_dwordx4 v[8:11], v[8:9], off offset:320
	s_and_saveexec_b64 s[24:25], s[40:41]
	s_cbranch_execz .LBB0_157
	v_lshl_add_u64 v[4:5], v[90:91], 0, v[74:75]
	global_load_dwordx4 v[4:7], v[4:5], off offset:832

; #define LAS __attribute__((address_space(3)))
; __device__ __forceinline__ f32x4 sigm4(f32x4 x) { return (f32x4){sigm(x[0]), sigm(x[1]), sigm(x[2]), sigm(x[3])}; }
; template <int CTRL> __device__ __forceinline__ float dpp0(float x) { return __builtin_bit_cast(float, __builtin_amdgcn_update_dpp(0, __builtin_bit_cast(int, x), CTRL, 0xf, 0xf, true)); }
; __device__ __forceinline__ float row16_scan(float x) { x += dpp0<0x111>(x); x += dpp0<0x112>(x); x += dpp0<0x114>(x); x += dpp0<0x118>(x); return x; }
; __device__ __forceinline__ void rw_scan(LAS unsigned char* L, const bf16_t* Rg, const bf16_t* Kg, const bf16_t* Vg, const bf16_t* VF, const bf16_t* LO, const bf16_t* wlbT, const bf16_t* albT, const bf16_t* vlbT, ...
;     ...
;                 float bs = 0.f;
; #pragma unroll
;                 for (int tl = 0; tl < 2; ++tl) { const int td = 2 * half + tl; const int c4 = td * 16 + 4 * fq;
;                     const f32x4 lw = sigm4(*(const LAS f32x4*)(CSTb + c4) + accw[tl]) * (-0.6065306597126334f * 1.4426950408889634f);
;                     f32x4 cl;
; #pragma unroll
;                     for (int r = 0; r < 4; ++r) cl[r] = row16_scan(lw[r]);
;                     const f32x4 ep = (f32x4){__builtin_amdgcn_exp2f(cl[0]), __builtin_amdgcn_exp2f(cl[1]), __builtin_amdgcn_exp2f(cl[2]), __builtin_amdgcn_exp2f(cl[3])};
;                     f32x4 epL, em, en;
; #pragma unroll
;                     for (int r = 0; r < 4; ++r) { epL[r] = __shfl(ep[r], (lane & 48) | 15); const float sh = dpp0<0x111>(ep[r]); em[r] = (fr == 0) ? 1.f : sh; en[r] = __builtin_amdgcn_rcpf(ep[r]); }
;                     const f32x4 eL = epL * en;
;                     const f32x4 a4 = sigm4(*(const LAS f32x4*)(CSTb + 128 + c4) + acca[tl]);
;                     const f32x4 kr = tl ? krs1 : krs0; const f32x4 kk4 = kr * *(const LAS f32x4*)(CSTb + 192 + c4) * inv;
;                     const f32x4 kd4 = kr * (1.f + (a4 - 1.f) * *(const LAS f32x4*)(CSTb + 256 + c4)); const f32x4 b4 = kk4 * a4; const f32x4 r4 = tl ? r4s1 : r4s0;
;                     if (ti == q) { const f32x4 rk = r4 * kd4 * *(const LAS f32x4*)(CSTb + 320 + c4); bs += (rk[0] + rk[1]) + (rk[2] + rk[3]); }
.LBB0_163:
	v_cndmask_b32_e64 v2, v123, v121, s[46:47]
	v_cndmask_b32_e64 v3, v122, v120, s[46:47]
	v_lshlrev_b32_e32 v124, 16, v2
	v_and_b32_e32 v125, 0xffff0000, v2
	v_and_or_b32 v2, v200, 64, v64
	s_waitcnt lgkmcnt(1)
	v_pk_add_f32 v[56:57], v[56:57], v[126:127]
	v_lshlrev_b32_e32 v122, 16, v3
	v_and_b32_e32 v123, 0xffff0000, v3
	v_lshl_or_b32 v3, v2, 2, 60
	v_mul_f32_e32 v2, 0xbfb8aa3b, v56
	v_exp_f32_e32 v2, v2
	v_mul_f32_e32 v56, 0xbfb8aa3b, v57
	v_exp_f32_e32 v75, v56
	v_pk_add_f32 v[56:57], v[58:59], v[128:129]
	v_add_f32_e32 v2, 1.0, v2
	v_rcp_f32_e32 v2, v2
	v_mul_f32_e32 v56, 0xbfb8aa3b, v56
	v_exp_f32_e32 v56, v56
	v_add_f32_e32 v58, 1.0, v75
	v_mul_f32_e32 v57, 0xbfb8aa3b, v57
	v_rcp_f32_e32 v58, v58
	v_exp_f32_e32 v57, v57
	v_mul_f32_e32 v59, 0xbf60028a, v2
	v_add_f32_e32 v56, 1.0, v56
	v_rcp_f32_e32 v56, v56
	v_mov_b32_dpp v59, v59 row_shr:1 row_mask:0xf bank_mask:0xf bound_ctrl:1
	v_fmac_f32_e32 v59, 0xbf60028a, v2
	v_add_f32_e32 v57, 1.0, v57
	v_rcp_f32_e32 v57, v57
	v_add_f32_dpp v2, v59, v59 row_shr:2 row_mask:0xf bank_mask:0xf bound_ctrl:1
	v_mul_f32_e32 v59, 0xbf60028a, v58
	s_waitcnt lgkmcnt(0)
	v_pk_add_f32 v[52:53], v[52:53], v[130:131]
	v_add_f32_dpp v2, v2, v2 row_shr:4 row_mask:0xf bank_mask:0xf bound_ctrl:1
	v_mov_b32_dpp v59, v59 row_shr:1 row_mask:0xf bank_mask:0xf bound_ctrl:1
	v_fmac_f32_e32 v59, 0xbf60028a, v58
	v_mul_f32_e32 v52, 0xbfb8aa3b, v52
	v_add_f32_dpp v2, v2, v2 row_shr:8 row_mask:0xf bank_mask:0xf bound_ctrl:1
	v_add_f32_dpp v58, v59, v59 row_shr:2 row_mask:0xf bank_mask:0xf bound_ctrl:1
	v_mul_f32_e32 v59, 0xbf60028a, v56
	v_exp_f32_e32 v126, v2
	v_add_f32_dpp v58, v58, v58 row_shr:4 row_mask:0xf bank_mask:0xf bound_ctrl:1
	v_mov_b32_dpp v59, v59 row_shr:1 row_mask:0xf bank_mask:0xf bound_ctrl:1
	v_fmac_f32_e32 v59, 0xbf60028a, v56
	v_add_f32_dpp v58, v58, v58 row_shr:8 row_mask:0xf bank_mask:0xf bound_ctrl:1
	v_exp_f32_e32 v127, v58
	v_add_f32_dpp v56, v59, v59 row_shr:2 row_mask:0xf bank_mask:0xf bound_ctrl:1
	v_mul_f32_e32 v59, 0xbf60028a, v57
	v_lshlrev_b32_e32 v120, 16, v118
	v_add_f32_dpp v56, v56, v56 row_shr:4 row_mask:0xf bank_mask:0xf bound_ctrl:1
	v_mov_b32_dpp v59, v59 row_shr:1 row_mask:0xf bank_mask:0xf bound_ctrl:1
	v_fmac_f32_e32 v59, 0xbf60028a, v57
	v_add_f32_dpp v56, v56, v56 row_shr:8 row_mask:0xf bank_mask:0xf bound_ctrl:1
	v_exp_f32_e32 v128, v56
	v_add_f32_dpp v57, v59, v59 row_shr:2 row_mask:0xf bank_mask:0xf bound_ctrl:1
	v_exp_f32_e32 v59, v52
	v_mul_f32_e32 v52, 0xbfb8aa3b, v53
	v_exp_f32_e32 v75, v52
	v_pk_add_f32 v[52:53], v[54:55], v[132:133]
	v_add_f32_dpp v57, v57, v57 row_shr:4 row_mask:0xf bank_mask:0xf bound_ctrl:1
	v_mul_f32_e32 v52, 0xbfb8aa3b, v52
	v_exp_f32_e32 v52, v52
	v_mul_f32_e32 v53, 0xbfb8aa3b, v53
	v_exp_f32_e32 v53, v53
	v_add_f32_dpp v57, v57, v57 row_shr:8 row_mask:0xf bank_mask:0xf bound_ctrl:1
	v_exp_f32_e32 v129, v57
	v_add_f32_e32 v54, 1.0, v59
	v_add_f32_e32 v52, 1.0, v52
	v_rcp_f32_e32 v134, v54
	v_add_f32_e32 v54, 1.0, v75
	v_rcp_f32_e32 v136, v52
	v_add_f32_e32 v52, 1.0, v53
	v_rcp_f32_e32 v135, v54
	v_rcp_f32_e32 v137, v52
	ds_read_b128 v[52:55], v69 offset:24320
	ds_read_b128 v[130:133], v69 offset:24576
	ds_bpermute_b32 v56, v3, v126
	ds_bpermute_b32 v57, v3, v127
	ds_bpermute_b32 v58, v3, v128
	ds_bpermute_b32 v59, v3, v129
	v_pk_add_f32 v[198:199], v[136:137], -1.0 op_sel_hi:[1,0]
	v_pk_add_f32 v[202:203], v[134:135], -1.0 op_sel_hi:[1,0]
	s_waitcnt lgkmcnt(4)
	v_pk_fma_f32 v[132:133], v[132:133], v[198:199], 1.0 op_sel_hi:[1,1,0]
	v_pk_fma_f32 v[198:199], v[130:131], v[202:203], 1.0 op_sel_hi:[1,1,0]
	v_and_b32_e32 v121, 0xffff0000, v118
	v_lshlrev_b32_e32 v118, 16, v119
	v_and_b32_e32 v119, 0xffff0000, v119
	v_mov_b32_dpp v2, v126 row_shr:1 row_mask:0xf bank_mask:0xf bound_ctrl:1
	v_mov_b32_dpp v228, v127 row_shr:1 row_mask:0xf bank_mask:0xf bound_ctrl:1
	v_mov_b32_dpp v227, v128 row_shr:1 row_mask:0xf bank_mask:0xf bound_ctrl:1
	v_mov_b32_dpp v229, v129 row_shr:1 row_mask:0xf bank_mask:0xf bound_ctrl:1
	v_pk_mul_f32 v[130:131], v[132:133], v[124:125]
	v_pk_mul_f32 v[132:133], v[198:199], v[122:123]
	v_mov_b32_e32 v75, 0
	s_and_saveexec_b64 s[24:25], s[72:73]
	s_cbranch_execz .LBB0_165
	ds_read_b128 v[206:209], v69 offset:24832
	v_pk_mul_f32 v[198:199], v[130:131], v[118:119]
	v_pk_mul_f32 v[202:203], v[132:133], v[120:121]
	s_waitcnt lgkmcnt(0)
	v_pk_mul_f32 v[198:199], v[198:199], v[208:209]
	v_pk_mul_f32 v[202:203], v[202:203], v[206:207]
	s_nop 0
	v_pk_mov_b32 v[204:205], v[202:203], v[198:199] op_sel:[1,0]
	v_mov_b32_e32 v203, v199
	v_pk_add_f32 v[198:199], v[204:205], v[202:203]
	s_nop 0
	v_add_f32_e32 v75, v198, v199
	v_add_f32_e32 v75, 0, v75

; #define LAS __attribute__((address_space(3)))
; __device__ __forceinline__ unsigned cvt_pk_bf16(float lo, float hi) { const f32x2_t v = {lo, hi}; const bf16x2_t b = __builtin_convertvector(v, bf16x2_t); return __builtin_bit_cast(unsigned, b); }
; __device__ __forceinline__ u32x2 pk4(f32x4 x) { u32x2 w; w.x = cvt_pk_bf16(x[0], x[1]); w.y = cvt_pk_bf16(x[2], x[3]); return w; }
; __device__ __forceinline__ void rw_scan(LAS unsigned char* L, const bf16_t* Rg, const bf16_t* Kg, const bf16_t* Vg, const bf16_t* VF, const bf16_t* LO, const bf16_t* wlbT, const bf16_t* albT, const bf16_t* vlbT, ...
;     ...
;                     const int p4 = 32 * (td >> 1) + 8 * fq + 4 * (td & 1);
;                     *(LAS u32x2*)(KQ + irow * 72 + p4) = pk4(kk4 * em); *(LAS u32x2*)(RQ + irow * 72 + p4) = pk4(r4 * ep);
;                     *(LAS u32x2*)(BD + irow * 72 + p4) = pk4(b4 * en); *(LAS u32x2*)(KD + irow * 72 + p4) = pk4(kd4 * en);
;                     const f32x4 bl = b4 * eL, kl = kd4 * eL;
; #pragma unroll
;                     for (int r = 0; r < 4; ++r) *(LAS unsigned*)(W2 + (c4 + r) * 136 + ti * 32 + 8 * (fr >> 2) + 2 * (fr & 3)) = cvt_pk_bf16(bl[r], kl[r]);
;                     if (fr == 15) *(LAS f32x4*)(LLs + ti * 64 + c4) = epL;
;                 }
;                 if (ti == q) { bs += __shfl_xor(bs, 16); bs += __shfl_xor(bs, 32);
;                     if (fq == 0) BON2[((size_t)(g * 2 + half) * T_ + rowcur) * 16 + h] = bs; }
.LBB0_169:
	s_or_b64 exec, exec, s[24:25]
	v_mov_b32_e32 v3, v2
	v_pk_mul_f32 v[46:47], v[46:47], v[58:59]
	v_pk_mul_f32 v[44:45], v[44:45], v[56:57]
	v_mov_b32_e32 v56, v2
	v_mov_b32_e32 v57, v2
	v_cndmask_b32_e64 v128, v125, 1.0, s[58:59]
	v_cndmask_b32_e64 v129, v126, 1.0, s[58:59]
	v_cndmask_b32_e64 v124, v124, 1.0, s[58:59]
	v_cndmask_b32_e64 v125, v127, 1.0, s[58:59]
	v_pk_mul_f32 v[46:47], v[56:57], v[46:47]
	v_pk_mul_f32 v[2:3], v[2:3], v[44:45]
	v_rcp_f32_e32 v130, v112
	v_rcp_f32_e32 v131, v113
	v_rcp_f32_e32 v132, v114
	v_rcp_f32_e32 v133, v115
	v_pk_mul_f32 v[44:45], v[46:47], v[122:123]
	v_pk_mul_f32 v[56:57], v[2:3], v[120:121]
	v_pk_mul_f32 v[46:47], v[124:125], v[46:47]
	v_pk_mul_f32 v[2:3], v[128:129], v[2:3]
	s_waitcnt lgkmcnt(2)
	v_pk_mul_f32 v[126:127], v[130:131], v[48:49]
	v_cvt_pk_bf16_f32 v2, v2, v3
	v_cvt_pk_bf16_f32 v3, v46, v47
	ds_write_b64 v179, v[2:3] offset:8
	v_pk_mul_f32 v[2:3], v[114:115], v[54:55]
	v_pk_mul_f32 v[46:47], v[112:113], v[52:53]
	v_pk_mul_f32 v[52:53], v[130:131], v[118:119]
	v_cvt_pk_bf16_f32 v46, v46, v47
	v_cvt_pk_bf16_f32 v47, v2, v3
	ds_write_b64 v180, v[46:47] offset:8
	v_pk_mul_f32 v[2:3], v[132:133], v[44:45]
	v_pk_mul_f32 v[46:47], v[130:131], v[56:57]
	s_waitcnt lgkmcnt(2)
	v_pk_mul_f32 v[134:135], v[132:133], v[50:51]
	v_cvt_pk_bf16_f32 v46, v46, v47
	v_cvt_pk_bf16_f32 v47, v2, v3
	v_pk_mul_f32 v[2:3], v[132:133], v[116:117]
	v_cvt_pk_bf16_f32 v52, v52, v53
	v_cvt_pk_bf16_f32 v53, v2, v3
	v_add_u32_e32 v2, 8, v145
	ds_write2st64_b64 v2, v[46:47], v[52:53] offset0:49 offset1:67
	v_pk_mul_f32 v[2:3], v[134:135], v[44:45]
	v_pk_mul_f32 v[44:45], v[126:127], v[56:57]
	v_pk_mul_f32 v[52:53], v[126:127], v[118:119]
	v_pk_mul_f32 v[46:47], v[134:135], v[116:117]
	v_cvt_pk_bf16_f32 v44, v44, v52
	v_cvt_pk_bf16_f32 v45, v45, v53
	v_add_u32_e32 v52, 0x1000, v223
	ds_write2_b32 v52, v44, v45 offset0:64 offset1:132
	v_cvt_pk_bf16_f32 v2, v2, v46
	v_cvt_pk_bf16_f32 v3, v3, v47
	v_add_u32_e32 v44, 0x1200, v223
	ds_write2_b32 v44, v2, v3 offset0:72 offset1:140
	s_and_saveexec_b64 s[24:25], s[60:61]
	ds_write_b128 v181, v[48:51] offset:64
	s_or_b64 exec, exec, s[24:25]
	s_and_saveexec_b64 s[24:25], s[72:73]
	s_cbranch_execz .LBB0_174
	v_mov_b32_e32 v1, v75
	s_nop 1
	v_permlane16_swap_b32_e32 v75, v1
	v_add_f32_e32 v1, v75, v1
	v_mov_b32_e32 v2, v1
	s_nop 1
	v_permlane32_swap_b32_e32 v1, v2
	s_and_b64 exec, exec, s[48:49]
	s_cbranch_execz .LBB0_174
	v_lshlrev_b64 v[44:45], 6, v[94:95]
	v_lshl_add_u64 v[44:45], v[82:83], 0, v[44:45]
	s_waitcnt lgkmcnt(0)
	v_add_f32_e32 v1, v1, v2
	global_store_dword v[44:45], v1, off

; #define LAS __attribute__((address_space(3)))
; __device__ __forceinline__ void rw_scan(LAS unsigned char* L, const bf16_t* Rg, const bf16_t* Kg, const bf16_t* Vg, const bf16_t* VF, const bf16_t* LO, const bf16_t* wlbT, const bf16_t* albT, const bf16_t* vlbT, ...
;     ...
;             if (m < 256) { const int sc = wid >> 1;
; #pragma unroll
;                 for (int ml = 0; ml < 3; ++ml) { const int mat = (wid & 1) ? ml + 1 : 0; if ((wid & 1) == 0 && ml > 0) break;     const LAS bf16_t* Am = (mat < 2) ? KQ : RQ; const LAS bf16_t* Bm = (mat & 1) ? KD : BD;
;                     f32x4 acc = {0.f, 0.f, 0.f, 0.f};
;                     acc = mma16(lfrag(Am, 72, sc * 16 + fr, 8 * fq), lfrag(Bm, 72, sc * 16 + fr, 8 * fq), acc);
;                     acc = mma16(lfrag(Am, 72, sc * 16 + fr, 32 + 8 * fq), lfrag(Bm, 72, sc * 16 + fr, 32 + 8 * fq), acc);
; #pragma unroll
;                     for (int r = 0; r < 4; ++r) { const int t = 4 * fq + r, sidx = fr; const bool keep = (mat < 2) ? (sidx < t) : (sidx <= t); const float val = keep ? acc[r] : 0.f;
;                         if (mat == 0) MM[(sc * 16 + t) * 20 + sidx] = val;
;                         else if (mat == 1) NA[(sc * 16 + t) * 32 + 8 * (sidx >> 2) + 4 + (sidx & 3)] = f2bf(val);
;                         else if (mat == 2) AR[(sc * 16 + t) * 40 + 8 * (sidx >> 2) + 2 * (sidx & 3)] = f2bf(val);
;                         else AR[(sc * 16 + t) * 40 + 8 * (sidx >> 2) + 2 * (sidx & 3) + 1] = f2bf(val); } }
;                 if ((wid & 1) == 0) { asm volatile("" ::: "memory");
;                     const int c = lane & 15; float tcol[16];
; #pragma unroll
;                     for (int i = 0; i < 16; ++i) { float acc0 = (i == c) ? 1.f : 0.f, acc1 = 0.f;
; #pragma unroll
;                         for (int j4 = 0; j4 < 4; ++j4) { if (j4 * 4 < i) { const f32x4 m4 = *(const LAS f32x4*)(MM + (sc * 16 + i) * 20 + j4 * 4);
; #pragma unroll
;                                 for (int jr = 0; jr < 4; ++jr) { const int j = j4 * 4 + jr; if (j < i) { if (jr & 1) acc1 -= m4[jr] * tcol[j]; else acc0 -= m4[jr] * tcol[j]; } } } }
;                         tcol[i] = acc0 + acc1; }
;                     if (lane < 16) {
; #pragma unroll
;                         for (int i = 0; i < 16; ++i) TI[(sc * 16 + i) * 32 + 8 * (c >> 2) + (c & 3)] = f2bf(-tcol[i]); } }
.LBB0_182:
	s_waitcnt lgkmcnt(0)
	s_barrier
	s_and_b64 vcc, exec, s[74:75]
	s_cbranch_vccnz .LBB0_90
	s_and_b64 vcc, exec, s[50:51]
	s_cbranch_vccnz .Lp2_odd_h2
	ds_read_b128 v[212:215], v184
	ds_read_b128 v[216:219], v146
	ds_read_b128 v[230:233], v184 offset:64
	ds_read_b128 v[234:237], v146 offset:64
	s_waitcnt lgkmcnt(2)
	v_mfma_f32_16x16x32_bf16 v[40:43], v[212:215], v[216:219], 0
	s_waitcnt lgkmcnt(0)
	v_mfma_f32_16x16x32_bf16 v[40:43], v[230:233], v[234:237], v[40:43]
	s_and_saveexec_b64 s[24:25], s[48:49]
	s_nop 7
	v_readlane_b32 s2, v41, 0
	v_readlane_b32 s3, v42, 0
	v_readlane_b32 s4, v42, 1
	v_readlane_b32 s5, v43, 0
	v_readlane_b32 s6, v43, 1
	v_fma_f32 v44, -s2, v157, v158
	v_cvt_pk_bf16_f32 v1, -v44, v44
	ds_write_b16 v186, v1 offset:64
	v_readlane_b32 s7, v43, 2
	v_fma_f32 v45, -s3, v157, v160
	v_readlane_b32 s8, v40, 16
	v_fma_f32 v59, -s4, v44, 0
	v_add_f32_e32 v45, v45, v59
	v_cvt_pk_bf16_f32 v1, -v45, v45
	ds_write_b16 v186, v1 offset:128
	v_readlane_b32 s9, v40, 17
	v_fma_f32 v46, -s5, v157, v161
	v_readlane_b32 s10, v40, 18
	v_fma_f32 v73, -s6, v44, 0
	v_readlane_b32 s11, v40, 19
	v_fma_f32 v46, -s7, v45, v46
	v_add_f32_e32 v46, v46, v73
	v_cvt_pk_bf16_f32 v1, -v46, v46
	ds_write_b16 v186, v1 offset:192
	v_readlane_b32 s14, v41, 16
	v_fma_f32 v47, -s8, v157, v162
	v_readlane_b32 s98, v41, 17
	v_fma_f32 v59, -s9, v44, 0
	v_readlane_b32 s99, v41, 18
	v_fma_f32 v47, -s10, v45, v47
	v_readlane_b32 s2, v41, 19
	v_fma_f32 v59, -s11, v46, v59
	v_add_f32_e32 v47, v47, v59
	v_cvt_pk_bf16_f32 v1, -v47, v47
	ds_write_b16 v186, v1 offset:256
	v_readlane_b32 s3, v41, 20
	v_fma_f32 v48, -s14, v157, v163
	v_readlane_b32 s4, v42, 16
	v_fma_f32 v73, -s98, v44, 0
	v_readlane_b32 s5, v42, 17
	v_fma_f32 v48, -s99, v45, v48
	v_readlane_b32 s6, v42, 18
	v_fma_f32 v73, -s2, v46, v73
	v_readlane_b32 s7, v42, 19
	v_fma_f32 v48, -s3, v47, v48
	v_add_f32_e32 v48, v48, v73
	v_cvt_pk_bf16_f32 v1, -v48, v48
	ds_write_b16 v186, v1 offset:320
	v_readlane_b32 s8, v42, 20
	v_fma_f32 v49, -s4, v157, v164
	v_readlane_b32 s9, v42, 21
	v_fma_f32 v59, -s5, v44, 0
	v_readlane_b32 s10, v43, 16
	v_fma_f32 v49, -s6, v45, v49
	v_readlane_b32 s11, v43, 17
	v_fma_f32 v59, -s7, v46, v59
	v_readlane_b32 s14, v43, 18
	v_fma_f32 v49, -s8, v47, v49
	v_readlane_b32 s98, v43, 19
	v_fma_f32 v59, -s9, v48, v59
	v_add_f32_e32 v49, v49, v59
	v_cvt_pk_bf16_f32 v1, -v49, v49
	ds_write_b16 v186, v1 offset:384
	v_readlane_b32 s99, v43, 20
	v_fma_f32 v50, -s10, v157, v165
	v_readlane_b32 s2, v43, 21
	v_fma_f32 v73, -s11, v44, 0
	v_readlane_b32 s3, v43, 22
	v_fma_f32 v50, -s14, v45, v50
	v_readlane_b32 s4, v40, 32
	v_fma_f32 v73, -s98, v46, v73
	v_readlane_b32 s5, v40, 33
	v_fma_f32 v50, -s99, v47, v50
	v_readlane_b32 s6, v40, 34
	v_fma_f32 v73, -s2, v48, v73
	v_readlane_b32 s7, v40, 35
	v_fma_f32 v50, -s3, v49, v50
	v_add_f32_e32 v50, v50, v73
	v_cvt_pk_bf16_f32 v1, -v50, v50
	ds_write_b16 v186, v1 offset:448
	v_readlane_b32 s8, v40, 36
	v_fma_f32 v51, -s4, v157, v166
	v_readlane_b32 s9, v40, 37
	v_fma_f32 v59, -s5, v44, 0
	v_readlane_b32 s10, v40, 38
	v_fma_f32 v51, -s6, v45, v51
	v_readlane_b32 s11, v40, 39
	v_fma_f32 v59, -s7, v46, v59
	v_readlane_b32 s14, v41, 32
	v_fma_f32 v51, -s8, v47, v51
	v_readlane_b32 s98, v41, 33
	v_fma_f32 v59, -s9, v48, v59
	v_readlane_b32 s99, v41, 34
	v_fma_f32 v51, -s10, v49, v51
	v_readlane_b32 s2, v41, 35
	v_fma_f32 v59, -s11, v50, v59
	v_add_f32_e32 v51, v51, v59
	v_cvt_pk_bf16_f32 v1, -v51, v51
	ds_write_b16 v186, v1 offset:512
	v_readlane_b32 s3, v41, 36
	v_fma_f32 v52, -s14, v157, v167
	v_readlane_b32 s4, v41, 37
	v_fma_f32 v73, -s98, v44, 0
	v_readlane_b32 s5, v41, 38
	v_fma_f32 v52, -s99, v45, v52
	v_readlane_b32 s6, v41, 39
	v_fma_f32 v73, -s2, v46, v73
	v_readlane_b32 s7, v41, 40
	v_fma_f32 v52, -s3, v47, v52
	v_readlane_b32 s8, v42, 32
	v_fma_f32 v73, -s4, v48, v73
	v_readlane_b32 s9, v42, 33
	v_fma_f32 v52, -s5, v49, v52
	v_readlane_b32 s10, v42, 34
	v_fma_f32 v73, -s6, v50, v73
	v_readlane_b32 s11, v42, 35
	v_fma_f32 v52, -s7, v51, v52
	v_add_f32_e32 v52, v52, v73
	v_cvt_pk_bf16_f32 v1, -v52, v52
	ds_write_b16 v186, v1 offset:576
	v_readlane_b32 s14, v42, 36
	v_fma_f32 v53, -s8, v157, v168
	v_readlane_b32 s98, v42, 37
	v_fma_f32 v59, -s9, v44, 0
	v_readlane_b32 s99, v42, 38
	v_fma_f32 v53, -s10, v45, v53
	v_readlane_b32 s2, v42, 39
	v_fma_f32 v59, -s11, v46, v59
	v_readlane_b32 s3, v42, 40
	v_fma_f32 v53, -s14, v47, v53
	v_readlane_b32 s4, v42, 41
	v_fma_f32 v59, -s98, v48, v59
	v_readlane_b32 s5, v43, 32
	v_fma_f32 v53, -s99, v49, v53
	v_readlane_b32 s6, v43, 33
	v_fma_f32 v59, -s2, v50, v59
	v_readlane_b32 s7, v43, 34
	v_fma_f32 v53, -s3, v51, v53
	v_readlane_b32 s8, v43, 35
	v_fma_f32 v59, -s4, v52, v59
	v_add_f32_e32 v53, v53, v59
	v_cvt_pk_bf16_f32 v1, -v53, v53
	ds_write_b16 v186, v1 offset:640
	v_readlane_b32 s9, v43, 36
	v_fma_f32 v54, -s5, v157, v169
	v_readlane_b32 s10, v43, 37
	v_fma_f32 v73, -s6, v44, 0
	v_readlane_b32 s11, v43, 38
	v_fma_f32 v54, -s7, v45, v54
	v_readlane_b32 s14, v43, 39
	v_fma_f32 v73, -s8, v46, v73
	v_readlane_b32 s98, v43, 40
	v_fma_f32 v54, -s9, v47, v54
	v_readlane_b32 s99, v43, 41
	v_fma_f32 v73, -s10, v48, v73
	v_readlane_b32 s2, v43, 42
	v_fma_f32 v54, -s11, v49, v54
	v_readlane_b32 s3, v40, 48
	v_fma_f32 v73, -s14, v50, v73
	v_readlane_b32 s4, v40, 49
	v_fma_f32 v54, -s98, v51, v54
	v_readlane_b32 s5, v40, 50
	v_fma_f32 v73, -s99, v52, v73
	v_readlane_b32 s6, v40, 51
	v_fma_f32 v54, -s2, v53, v54
	v_add_f32_e32 v54, v54, v73
	v_cvt_pk_bf16_f32 v1, -v54, v54
	ds_write_b16 v186, v1 offset:704
	v_readlane_b32 s7, v40, 52
	v_fma_f32 v55, -s3, v157, v170
	v_readlane_b32 s8, v40, 53
; #define LAS __attribute__((address_space(3)))
; __device__ __forceinline__ bf16_t f2bf(float f) { return (bf16_t)(cvt_pk_bf16(f, 0.f) & 0xffffu); }
; __device__ __forceinline__ f32x4 mma16(bf16x8 a, bf16x8 b, f32x4 c) { return __builtin_amdgcn_mfma_f32_16x16x32_bf16(a, b, c, 0, 0, 0); }
; __device__ __forceinline__ void rw_scan(LAS unsigned char* L, const bf16_t* Rg, const bf16_t* Kg, const bf16_t* Vg, const bf16_t* VF, const bf16_t* LO, const bf16_t* wlbT, const bf16_t* albT, const bf16_t* vlbT, ...
;     ...
;                 for (int ml = 0; ml < 3; ++ml) { const int mat = (wid & 1) ? ml + 1 : 0; if ((wid & 1) == 0 && ml > 0) break;     const LAS bf16_t* Am = (mat < 2) ? KQ : RQ; const LAS bf16_t* Bm = (mat & 1) ? KD : BD;
;                     f32x4 acc = {0.f, 0.f, 0.f, 0.f};
;                     acc = mma16(lfrag(Am, 72, sc * 16 + fr, 8 * fq), lfrag(Bm, 72, sc * 16 + fr, 8 * fq), acc);
;                     acc = mma16(lfrag(Am, 72, sc * 16 + fr, 32 + 8 * fq), lfrag(Bm, 72, sc * 16 + fr, 32 + 8 * fq), acc);
; #pragma unroll
;                     for (int r = 0; r < 4; ++r) { const int t = 4 * fq + r, sidx = fr; const bool keep = (mat < 2) ? (sidx < t) : (sidx <= t); const float val = keep ? acc[r] : 0.f;
;                         if (mat == 0) MM[(sc * 16 + t) * 20 + sidx] = val;
;                         else if (mat == 1) NA[(sc * 16 + t) * 32 + 8 * (sidx >> 2) + 4 + (sidx & 3)] = f2bf(val);
;                         else if (mat == 2) AR[(sc * 16 + t) * 40 + 8 * (sidx >> 2) + 2 * (sidx & 3)] = f2bf(val);
;                         else AR[(sc * 16 + t) * 40 + 8 * (sidx >> 2) + 2 * (sidx & 3) + 1] = f2bf(val); } }
;     ...
;                     for (int i = 0; i < 16; ++i) { float acc0 = (i == c) ? 1.f : 0.f, acc1 = 0.f;
; #pragma unroll
;                         for (int j4 = 0; j4 < 4; ++j4) { if (j4 * 4 < i) { const f32x4 m4 = *(const LAS f32x4*)(MM + (sc * 16 + i) * 20 + j4 * 4);
; #pragma unroll
;                                 for (int jr = 0; jr < 4; ++jr) { const int j = j4 * 4 + jr; if (j < i) { if (jr & 1) acc1 -= m4[jr] * tcol[j]; else acc0 -= m4[jr] * tcol[j]; } } } }
;                         tcol[i] = acc0 + acc1; }
;                     if (lane < 16) {
; #pragma unroll
;                         for (int i = 0; i < 16; ++i) TI[(sc * 16 + i) * 32 + 8 * (c >> 2) + (c & 3)] = f2bf(-tcol[i]); } }
	v_fma_f32 v59, -s4, v44, 0
	v_readlane_b32 s9, v40, 54
	v_fma_f32 v55, -s5, v45, v55
	v_readlane_b32 s10, v40, 55
	v_fma_f32 v59, -s6, v46, v59
	v_readlane_b32 s11, v40, 56
	v_fma_f32 v55, -s7, v47, v55
	v_readlane_b32 s14, v40, 57
	v_fma_f32 v59, -s8, v48, v59
	v_readlane_b32 s98, v40, 58
	v_fma_f32 v55, -s9, v49, v55
	v_readlane_b32 s99, v40, 59
	v_fma_f32 v59, -s10, v50, v59
	v_readlane_b32 s2, v41, 48
	v_fma_f32 v55, -s11, v51, v55
	v_readlane_b32 s3, v41, 49
	v_fma_f32 v59, -s14, v52, v59
	v_readlane_b32 s4, v41, 50
	v_fma_f32 v55, -s98, v53, v55
	v_readlane_b32 s5, v41, 51
	v_fma_f32 v59, -s99, v54, v59
	v_add_f32_e32 v55, v55, v59
	v_cvt_pk_bf16_f32 v1, -v55, v55
	ds_write_b16 v186, v1 offset:768
	v_readlane_b32 s6, v41, 52
	v_fma_f32 v56, -s2, v157, v171
	v_readlane_b32 s7, v41, 53
	v_fma_f32 v73, -s3, v44, 0
	v_readlane_b32 s8, v41, 54
	v_fma_f32 v56, -s4, v45, v56
	v_readlane_b32 s9, v41, 55
	v_fma_f32 v73, -s5, v46, v73
	v_readlane_b32 s10, v41, 56
	v_fma_f32 v56, -s6, v47, v56
	v_readlane_b32 s11, v41, 57
	v_fma_f32 v73, -s7, v48, v73
	v_readlane_b32 s14, v41, 58
	v_fma_f32 v56, -s8, v49, v56
	v_readlane_b32 s98, v41, 59
	v_fma_f32 v73, -s9, v50, v73
	v_readlane_b32 s99, v41, 60
	v_fma_f32 v56, -s10, v51, v56
	v_readlane_b32 s2, v42, 48
	v_fma_f32 v73, -s11, v52, v73
	v_readlane_b32 s3, v42, 49
	v_fma_f32 v56, -s14, v53, v56
	v_readlane_b32 s4, v42, 50
	v_fma_f32 v73, -s98, v54, v73
	v_readlane_b32 s5, v42, 51
	v_fma_f32 v56, -s99, v55, v56
	v_add_f32_e32 v56, v56, v73
	v_cvt_pk_bf16_f32 v1, -v56, v56
	ds_write_b16 v186, v1 offset:832
	v_readlane_b32 s6, v42, 52
	v_fma_f32 v57, -s2, v157, v172
	v_readlane_b32 s7, v42, 53
	v_fma_f32 v59, -s3, v44, 0
	v_readlane_b32 s8, v42, 54
	v_fma_f32 v57, -s4, v45, v57
	v_readlane_b32 s9, v42, 55
	v_fma_f32 v59, -s5, v46, v59
	v_readlane_b32 s10, v42, 56
	v_fma_f32 v57, -s6, v47, v57
	v_readlane_b32 s11, v42, 57
	v_fma_f32 v59, -s7, v48, v59
	v_readlane_b32 s14, v42, 58
	v_fma_f32 v57, -s8, v49, v57
	v_readlane_b32 s98, v42, 59
	v_fma_f32 v59, -s9, v50, v59
	v_readlane_b32 s99, v42, 60
	v_fma_f32 v57, -s10, v51, v57
	v_readlane_b32 s2, v42, 61
	v_fma_f32 v59, -s11, v52, v59
	v_readlane_b32 s3, v43, 48
	v_fma_f32 v57, -s14, v53, v57
	v_readlane_b32 s4, v43, 49
	v_fma_f32 v59, -s98, v54, v59
	v_readlane_b32 s5, v43, 50
	v_fma_f32 v57, -s99, v55, v57
	v_readlane_b32 s6, v43, 51
	v_fma_f32 v59, -s2, v56, v59
	v_add_f32_e32 v57, v57, v59
	v_cvt_pk_bf16_f32 v1, -v57, v57
	ds_write_b16 v186, v1 offset:896
	v_readlane_b32 s7, v43, 52
	v_fma_f32 v58, -s3, v157, v173
	v_readlane_b32 s8, v43, 53
	v_fma_f32 v73, -s4, v44, 0
	v_readlane_b32 s9, v43, 54
	v_fma_f32 v58, -s5, v45, v58
	v_readlane_b32 s10, v43, 55
	v_fma_f32 v73, -s6, v46, v73
	v_readlane_b32 s11, v43, 56
	v_fma_f32 v58, -s7, v47, v58
	v_readlane_b32 s14, v43, 57
	v_fma_f32 v73, -s8, v48, v73
	v_readlane_b32 s98, v43, 58
	v_fma_f32 v58, -s9, v49, v58
	v_readlane_b32 s99, v43, 59
	v_fma_f32 v73, -s10, v50, v73
	v_readlane_b32 s2, v43, 60
	v_fma_f32 v58, -s11, v51, v58
	v_readlane_b32 s3, v43, 61
	v_fma_f32 v73, -s14, v52, v73
	v_readlane_b32 s4, v43, 62
	v_fma_f32 v58, -s98, v53, v58
	v_fma_f32 v73, -s99, v54, v73
	v_fma_f32 v58, -s2, v55, v58
	v_fma_f32 v73, -s3, v56, v73
	v_fma_f32 v58, -s4, v57, v58
	v_add_f32_e32 v58, v58, v73
	v_cvt_pk_bf16_f32 v1, -v58, v58
	ds_write_b16 v186, v1 offset:960
	ds_write_b16 v186, v174
	s_or_b64 exec, exec, s[24:25]
	s_branch .LBB0_90
.Lp2_odd_h2:
	ds_read_b128 v[40:43], v184
	ds_read_b128 v[44:47], v156 offset:34304
	ds_read_b128 v[48:51], v185
	ds_read_b128 v[52:55], v156 offset:25088
	ds_read_b128 v[56:59], v184 offset:64
	ds_read_b128 v[212:215], v156 offset:34368
	ds_read_b128 v[216:219], v185 offset:64
	ds_read_b128 v[230:233], v156 offset:25152
	v_add_u32_e32 v2, v182, v148
	v_add_u32_e32 v3, v182, v150
	v_add_u32_e32 v73, v182, v152
	v_add_u32_e32 v75, v182, v155
	s_waitcnt lgkmcnt(6)
	v_mfma_f32_16x16x32_bf16 v[234:237], v[40:43], v[44:47], 0
	s_waitcnt lgkmcnt(4)
	v_mfma_f32_16x16x32_bf16 v[238:241], v[48:51], v[52:55], 0
	v_mfma_f32_16x16x32_bf16 v[246:249], v[48:51], v[44:47], 0
	s_waitcnt lgkmcnt(2)
	v_mfma_f32_16x16x32_bf16 v[234:237], v[56:59], v[212:215], v[234:237]
	s_waitcnt lgkmcnt(0)
	v_mfma_f32_16x16x32_bf16 v[238:241], v[216:219], v[230:233], v[238:241]
	v_mfma_f32_16x16x32_bf16 v[246:249], v[216:219], v[212:215], v[246:249]
	v_add_u32_e32 v44, v183, v147
	v_add_u32_e32 v45, v183, v149
	v_add_u32_e32 v46, v183, v151
	v_add_u32_e32 v47, v183, v153
	s_nop 1
	v_cndmask_b32_e64 v1, 0, v234, s[52:53]
	v_cvt_pk_bf16_f32 v1, v1, v1
	ds_write_b16 v44, v1
	v_cndmask_b32_e64 v1, v235, 0, s[54:55]
	v_cvt_pk_bf16_f32 v1, v1, v1
	ds_write_b16 v45, v1
	v_cndmask_b32_e64 v1, 0, v236, s[56:57]
	v_cvt_pk_bf16_f32 v1, v1, v1
	ds_write_b16 v46, v1
	v_cndmask_b32_e64 v1, 0, v237, s[62:63]
	v_cvt_pk_bf16_f32 v1, v1, v1
	ds_write_b16 v47, v1
	v_cvt_pk_bf16_f32 v1, v238, v238
	v_cndmask_b32_e64 v1, v1, 0, s[54:55]
	ds_write_b16 v2, v1
	v_cvt_pk_bf16_f32 v1, v239, v239
	v_cndmask_b32_e64 v1, v1, 0, s[64:65]
	ds_write_b16 v3, v1
	v_cvt_pk_bf16_f32 v1, v240, v240
	v_cndmask_b32_e64 v1, v1, 0, s[66:67]
	ds_write_b16 v73, v1
	v_cvt_pk_bf16_f32 v1, v241, v241
	v_cndmask_b32_e64 v1, v1, 0, s[68:69]
	ds_write_b16 v75, v1
	v_cvt_pk_bf16_f32 v1, v246, v246
	v_cndmask_b32_e64 v1, v1, 0, s[54:55]
	ds_write_b16 v2, v1 offset:2
	v_cvt_pk_bf16_f32 v1, v247, v247
	v_cndmask_b32_e64 v1, v1, 0, s[64:65]
	ds_write_b16 v3, v1 offset:2
	v_cvt_pk_bf16_f32 v1, v248, v248
	v_cndmask_b32_e64 v1, v1, 0, s[66:67]
	ds_write_b16 v73, v1 offset:2
	v_cvt_pk_bf16_f32 v1, v249, v249
	v_cndmask_b32_e64 v1, v1, 0, s[68:69]
	ds_write_b16 v75, v1 offset:2
	s_branch .LBB0_90
